# cross-lane reductions moved off LDS: q/k-norm sums via v_permlane16/32_swap (16 ds_bpermute round trips per q/k unit gone), sub-LayerNorm 16-lane butterflies via DPP adds (16 round trips per block epi
# baseline (speedup 1.0000x reference)
; __device__ __forceinline__ u32x4 pack8f(const f32x4 a, const f32x4 b) { u32x4 w; w.x = cvt_pk_bf16(a[0], a[1]); w.y = cvt_pk_bf16(a[2], a[3]); w.z = cvt_pk_bf16(b[0], b[1]); w.w = cvt_pk_bf16(b[2], b[3]); return w; }
;     __device__ __forceinline__ void operator()(f32x4 (&acc)[2][2][4][2], const Unit& u, int wr, int wc, int fr, int fq) const {
;     ...
;                 for (int m = 0; m < 4; ++m) {
;                     float ss = 0.f;
; #pragma unroll
;                     for (int bj = 0; bj < 2; ++bj)
; #pragma unroll
;                         for (int n = 0; n < 2; ++n) { const f32x4 x = acc[ai][bj][m][n]; ss += (x[0] * x[0] + x[1] * x[1]) + (x[2] * x[2] + x[3] * x[3]); }
;                     ss += __shfl_xor(ss, 16); ss += __shfl_xor(ss, 32);
;                     const float sc = rsqrtf(ss * (1.f / 64.f) + EPS) * (isq ? C2 : 1.f);
;                     const int rl = rl0 + 128 * ai + 16 * m;
; #pragma unroll
;                     for (int bj = 0; bj < 2; ++bj) {
;                         const u32x4 w = pack8f(acc[ai][bj][m][0] * sc * gv[bj][0], acc[ai][bj][m][1] * sc * gv[bj][1]);
;                         if (isq) *(u32x4*)(Q + (size_t)(u.pm * 256 + rl) * AW + grp * 64 + 32 * bj + 8 * fq) = w;
;                         else *(u32x4*)(KI + kimg_off(b, grp >> 1, grp & 1, s0 + rl + NMETA, 32 * bj + 8 * fq)) = w;
;                     }
.LBB0_174:
	s_andn2_b64 vcc, exec, s[88:89]
	s_cbranch_vccnz .LBB0_239
	s_cmp_gt_i32 s10, 1
	s_cselect_b64 s[88:89], -1, 0
	s_cmp_lt_i32 s10, 2
	s_cselect_b64 vcc, -1, 0
	s_and_b64 s[90:91], vcc, exec
	s_cselect_b32 s11, s27, s29
	s_cselect_b32 s18, s26, s28
	v_lshlrev_b32_e32 v168, 3, v200
	v_mov_b32_e32 v130, s18
	v_mov_b32_e32 v131, s11
	v_ashrrev_i32_e32 v169, 31, v168
	v_lshl_add_u64 v[134:135], v[168:169], 2, v[130:131]
	global_load_dwordx4 v[138:141], v[134:135], off offset:16
	global_load_dwordx4 v[142:145], v[134:135], off
	global_load_dwordx4 v[130:133], v[134:135], off offset:144
	s_nop 0
	global_load_dwordx4 v[134:137], v[134:135], off offset:128
	s_lshl_b32 s10, s10, 2
	v_and_b32_e32 v167, 64, v198
	s_and_b32 s10, s10, 4
	v_xor_b32_e32 v154, 16, v198
	v_add_u32_e32 v167, 64, v167
	s_or_b32 s22, s10, s55
	v_cmp_lt_i32_e64 s[10:11], v154, v167
	v_pk_mul_f32 v[170:171], v[128:129], v[128:129]
	v_pk_mul_f32 v[172:173], v[126:127], v[126:127]
	v_cndmask_b32_e64 v154, v198, v154, s[10:11]
	v_lshlrev_b32_e32 v174, 2, v154
	v_xor_b32_e32 v154, 32, v198
	v_pk_mov_b32 v[178:179], v[172:173], v[170:171] op_sel:[1,0]
	v_mov_b32_e32 v173, v171
	v_cmp_lt_i32_e64 s[10:11], v154, v167
	v_pk_add_f32 v[170:171], v[178:179], v[172:173]
	v_pk_mul_f32 v[172:173], v[124:125], v[124:125]
	v_pk_mul_f32 v[178:179], v[122:123], v[122:123]
	v_cndmask_b32_e64 v154, v198, v154, s[10:11]
	v_pk_mov_b32 v[180:181], v[178:179], v[172:173] op_sel:[1,0]
	v_mov_b32_e32 v179, v173
	v_lshlrev_b32_e32 v175, 2, v154
	v_lshlrev_b32_e32 v154, 2, v166
	v_pk_add_f32 v[172:173], v[180:181], v[178:179]
	v_and_b32_e32 v176, 56, v154
	v_mul_f32_e32 v154, v114, v114
	v_mul_f32_e32 v177, v115, v115
	v_pk_add_f32 v[170:171], v[170:171], v[170:171] op_sel:[0,1] op_sel_hi:[1,0]
	v_pk_add_f32 v[172:173], v[172:173], v[172:173] op_sel:[0,1] op_sel_hi:[1,0]
	v_mov_b32_e32 v171, v154
	v_mov_b32_e32 v173, v177
	v_mul_f32_e32 v154, v119, v119
	v_mul_f32_e32 v178, v116, v116
	v_pk_add_f32 v[170:171], v[170:171], v[172:173]
	v_pk_fma_f32 v[172:173], v[118:119], v[118:119], v[154:155] op_sel_hi:[1,1,0]
	v_mul_f32_e32 v154, v121, v121
	v_mul_f32_e32 v180, v117, v117
	v_mov_b32_e32 v173, v178
	v_pk_fma_f32 v[178:179], v[120:121], v[120:121], v[154:155] op_sel_hi:[1,1,0]
	v_cndmask_b32_e32 v167, 1.0, v199, vcc
	v_mov_b32_e32 v179, v180
	v_pk_add_f32 v[172:173], v[172:173], v[178:179]
	s_or_b32 s79, s83, 16
	v_pk_add_f32 v[170:171], v[170:171], v[172:173]
	s_and_b32 s10, s22, 6
	v_add_f32_e32 v154, v170, v171
	v_mov_b32_e32 v170, v154
	s_lshl_b32 s11, s81, 3
	s_or_b32 s10, s10, s11
	s_or_b32 s83, s10, s67
	s_nop 1
	v_permlane16_swap_b32 v170, v154
	v_add_f32_e32 v154, v154, v170
	v_mov_b32_e32 v170, v154
	s_nop 1
	v_permlane32_swap_b32 v170, v154
	v_add_f32_e32 v154, v154, v170
	v_fmamk_f32 v154, v154, 0x3c800000, v196
	v_cmp_gt_f32_e32 vcc, s65, v154
	v_mul_f32_e32 v170, 0x4b800000, v154
	s_nop 0
	v_cndmask_b32_e32 v154, v154, v170, vcc
	v_rsq_f32_e32 v154, v154
	s_nop 0
	v_mul_f32_e32 v170, 0x45800000, v154
	v_cndmask_b32_e32 v154, v154, v170, vcc
	v_mul_f32_e32 v170, v167, v154
	v_add_u32_e32 v154, s79, v166
	v_ashrrev_i32_e32 v172, 6, v154
	v_ashrrev_i32_e32 v173, 31, v172
	v_lshlrev_b32_e32 v154, 6, v154
	v_pk_mul_f32 v[126:127], v[126:127], v[170:171] op_sel_hi:[1,0]
	v_pk_mul_f32 v[128:129], v[128:129], v[170:171] op_sel_hi:[1,0]
	v_pk_mul_f32 v[122:123], v[122:123], v[170:171] op_sel_hi:[1,0]
	v_pk_mul_f32 v[124:125], v[124:125], v[170:171] op_sel_hi:[1,0]
	v_mad_i64_i32 v[172:173], s[10:11], s83, v197, v[172:173]
	v_and_b32_e32 v154, 0xfc0, v154
	s_waitcnt vmcnt(0)
	v_pk_mul_f32 v[128:129], v[144:145], v[128:129]
	v_pk_mul_f32 v[126:127], v[142:143], v[126:127]
	v_pk_mul_f32 v[178:179], v[140:141], v[124:125]
	v_pk_mul_f32 v[124:125], v[138:139], v[122:123]
	v_lshlrev_b64 v[172:173], 13, v[172:173]
	v_cvt_pk_bf16_f32 v122, v126, v127
	v_cvt_pk_bf16_f32 v123, v128, v129
	v_cvt_pk_bf16_f32 v124, v124, v125
	v_cvt_pk_bf16_f32 v125, v178, v179
	s_mov_b64 s[10:11], -1
	s_and_b64 vcc, exec, s[88:89]
	v_xor_b32_e32 v126, v168, v176
	v_lshlrev_b32_e32 v154, 1, v154
	s_cbranch_vccz .LBB0_177
	v_ashrrev_i32_e32 v127, 31, v126
	v_lshl_add_u64 v[128:129], s[48:49], 0, v[154:155]
	v_lshl_add_u64 v[128:129], v[126:127], 1, v[128:129]
	v_lshl_add_u64 v[128:129], v[128:129], 0, v[172:173]
	global_store_dwordx4 v[128:129], v[122:125], off
	s_mov_b64 s[10:11], 0

; __device__ __forceinline__ u32x4 pack8f(const f32x4 a, const f32x4 b) { u32x4 w; w.x = cvt_pk_bf16(a[0], a[1]); w.y = cvt_pk_bf16(a[2], a[3]); w.z = cvt_pk_bf16(b[0], b[1]); w.w = cvt_pk_bf16(b[2], b[3]); return w; }
;     __device__ __forceinline__ void operator()(f32x4 (&acc)[2][2][4][2], const Unit& u, int wr, int wc, int fr, int fq) const {
;     ...
;                 for (int m = 0; m < 4; ++m) {
;                     float ss = 0.f;
; #pragma unroll
;                     for (int bj = 0; bj < 2; ++bj)
; #pragma unroll
;                         for (int n = 0; n < 2; ++n) { const f32x4 x = acc[ai][bj][m][n]; ss += (x[0] * x[0] + x[1] * x[1]) + (x[2] * x[2] + x[3] * x[3]); }
;                     ss += __shfl_xor(ss, 16); ss += __shfl_xor(ss, 32);
;                     const float sc = rsqrtf(ss * (1.f / 64.f) + EPS) * (isq ? C2 : 1.f);
;                     const int rl = rl0 + 128 * ai + 16 * m;
; #pragma unroll
;                     for (int bj = 0; bj < 2; ++bj) {
;                         const u32x4 w = pack8f(acc[ai][bj][m][0] * sc * gv[bj][0], acc[ai][bj][m][1] * sc * gv[bj][1]);
;                         if (isq) *(u32x4*)(Q + (size_t)(u.pm * 256 + rl) * AW + grp * 64 + 32 * bj + 8 * fq) = w;
;                         else *(u32x4*)(KI + kimg_off(b, grp >> 1, grp & 1, s0 + rl + NMETA, 32 * bj + 8 * fq)) = w;
;                     }
.LBB0_183:
	s_nop 1
	v_pk_mul_f32 v[114:115], v[112:113], v[112:113]
	v_pk_mul_f32 v[116:117], v[110:111], v[110:111]
	v_mul_f32_e32 v119, v98, v98
	v_pk_mov_b32 v[120:121], v[116:117], v[114:115] op_sel:[1,0]
	v_mov_b32_e32 v117, v115
	v_pk_add_f32 v[114:115], v[120:121], v[116:117]
	v_pk_mul_f32 v[116:117], v[108:109], v[108:109]
	v_pk_mul_f32 v[120:121], v[106:107], v[106:107]
	v_pk_add_f32 v[114:115], v[114:115], v[114:115] op_sel:[0,1] op_sel_hi:[1,0]
	v_pk_mov_b32 v[122:123], v[120:121], v[116:117] op_sel:[1,0]
	v_mov_b32_e32 v121, v117
	v_pk_add_f32 v[116:117], v[122:123], v[120:121]
	v_mul_f32_e32 v120, v99, v99
	v_pk_add_f32 v[116:117], v[116:117], v[116:117] op_sel:[0,1] op_sel_hi:[1,0]
	v_mov_b32_e32 v115, v119
	v_mov_b32_e32 v117, v120
	v_pk_add_f32 v[114:115], v[114:115], v[116:117]
	v_mul_f32_e32 v116, v103, v103
	v_mul_f32_e32 v121, v100, v100
	v_pk_fma_f32 v[116:117], v[102:103], v[102:103], v[116:117] op_sel_hi:[1,1,0]
	v_mul_f32_e32 v120, v105, v105
	v_mul_f32_e32 v122, v101, v101
	v_mov_b32_e32 v117, v121
	v_pk_fma_f32 v[120:121], v[104:105], v[104:105], v[120:121] op_sel_hi:[1,1,0]
	s_mul_hi_i32 s89, s83, 0x42
	v_mov_b32_e32 v121, v122
	v_pk_add_f32 v[116:117], v[116:117], v[120:121]
	s_mul_i32 s88, s83, 0x42
	v_pk_add_f32 v[114:115], v[114:115], v[116:117]
	v_add_u32_e32 v117, 16, v166
	v_add_f32_e32 v114, v114, v115
	v_mov_b32_e32 v115, v114
	v_add_u32_e32 v119, s79, v117
	s_mov_b64 s[90:91], -1
	s_nop 1
	v_permlane16_swap_b32 v115, v114
	v_add_f32_e32 v114, v114, v115
	v_mov_b32_e32 v115, v114
	s_nop 1
	v_permlane32_swap_b32 v115, v114
	v_add_f32_e32 v114, v114, v115
	v_fmamk_f32 v114, v114, 0x3c800000, v196
	v_cmp_gt_f32_e32 vcc, s65, v114
	v_mul_f32_e32 v115, 0x4b800000, v114
	s_nop 0
	v_cndmask_b32_e32 v114, v114, v115, vcc
	v_rsq_f32_e32 v114, v114
	s_nop 0
	v_mul_f32_e32 v115, 0x45800000, v114
	v_cndmask_b32_e32 v114, v114, v115, vcc
	v_mul_f32_e32 v116, v167, v114
	v_ashrrev_i32_e32 v114, 6, v119
	v_ashrrev_i32_e32 v115, 31, v114
	v_lshlrev_b32_e32 v119, 6, v119
	v_pk_mul_f32 v[110:111], v[110:111], v[116:117] op_sel_hi:[1,0]
	v_pk_mul_f32 v[112:113], v[112:113], v[116:117] op_sel_hi:[1,0]
	v_pk_mul_f32 v[106:107], v[106:107], v[116:117] op_sel_hi:[1,0]
	v_pk_mul_f32 v[108:109], v[108:109], v[116:117] op_sel_hi:[1,0]
	v_lshl_add_u64 v[114:115], s[88:89], 0, v[114:115]
	v_and_b32_e32 v119, 0xfc0, v119
	v_pk_mul_f32 v[112:113], v[144:145], v[112:113]
	v_pk_mul_f32 v[110:111], v[142:143], v[110:111]
	v_pk_mul_f32 v[120:121], v[140:141], v[108:109]
	v_pk_mul_f32 v[108:109], v[138:139], v[106:107]
	v_lshlrev_b64 v[114:115], 13, v[114:115]
	v_cvt_pk_bf16_f32 v106, v110, v111
	v_cvt_pk_bf16_f32 v107, v112, v113
	v_cvt_pk_bf16_f32 v108, v108, v109
	v_cvt_pk_bf16_f32 v109, v120, v121
	s_and_b64 vcc, exec, s[10:11]
	v_lshlrev_b32_e32 v154, 1, v119
	s_cbranch_vccnz .LBB0_185
	v_ashrrev_i32_e32 v127, 31, v126
	v_lshl_add_u64 v[110:111], s[48:49], 0, v[154:155]
	v_lshl_add_u64 v[110:111], v[126:127], 1, v[110:111]
	v_lshl_add_u64 v[110:111], v[110:111], 0, v[114:115]
	s_mov_b64 s[90:91], 0
	global_store_dwordx4 v[110:111], v[106:109], off

; __device__ __forceinline__ u32x4 pack8f(const f32x4 a, const f32x4 b) { u32x4 w; w.x = cvt_pk_bf16(a[0], a[1]); w.y = cvt_pk_bf16(a[2], a[3]); w.z = cvt_pk_bf16(b[0], b[1]); w.w = cvt_pk_bf16(b[2], b[3]); return w; }
;     __device__ __forceinline__ void operator()(f32x4 (&acc)[2][2][4][2], const Unit& u, int wr, int wc, int fr, int fq) const {
;     ...
;                 for (int m = 0; m < 4; ++m) {
;                     float ss = 0.f;
; #pragma unroll
;                     for (int bj = 0; bj < 2; ++bj)
; #pragma unroll
;                         for (int n = 0; n < 2; ++n) { const f32x4 x = acc[ai][bj][m][n]; ss += (x[0] * x[0] + x[1] * x[1]) + (x[2] * x[2] + x[3] * x[3]); }
;                     ss += __shfl_xor(ss, 16); ss += __shfl_xor(ss, 32);
;                     const float sc = rsqrtf(ss * (1.f / 64.f) + EPS) * (isq ? C2 : 1.f);
;                     const int rl = rl0 + 128 * ai + 16 * m;
; #pragma unroll
;                     for (int bj = 0; bj < 2; ++bj) {
;                         const u32x4 w = pack8f(acc[ai][bj][m][0] * sc * gv[bj][0], acc[ai][bj][m][1] * sc * gv[bj][1]);
;                         if (isq) *(u32x4*)(Q + (size_t)(u.pm * 256 + rl) * AW + grp * 64 + 32 * bj + 8 * fq) = w;
;                         else *(u32x4*)(KI + kimg_off(b, grp >> 1, grp & 1, s0 + rl + NMETA, 32 * bj + 8 * fq)) = w;
;                     }
.LBB0_191:
	s_nop 1
	v_pk_mul_f32 v[98:99], v[96:97], v[96:97]
	v_pk_mul_f32 v[100:101], v[94:95], v[94:95]
	s_mov_b64 s[90:91], -1
	v_pk_mov_b32 v[102:103], v[100:101], v[98:99] op_sel:[1,0]
	v_mov_b32_e32 v101, v99
	v_pk_add_f32 v[98:99], v[102:103], v[100:101]
	v_pk_mul_f32 v[100:101], v[92:93], v[92:93]
	v_pk_mul_f32 v[102:103], v[90:91], v[90:91]
	v_pk_add_f32 v[98:99], v[98:99], v[98:99] op_sel:[0,1] op_sel_hi:[1,0]
	v_pk_mov_b32 v[104:105], v[102:103], v[100:101] op_sel:[1,0]
	v_mov_b32_e32 v103, v101
	v_pk_add_f32 v[100:101], v[104:105], v[102:103]
	v_mul_f32_e32 v102, v82, v82
	v_mul_f32_e32 v103, v83, v83
	v_pk_add_f32 v[100:101], v[100:101], v[100:101] op_sel:[0,1] op_sel_hi:[1,0]
	v_mov_b32_e32 v99, v102
	v_mov_b32_e32 v101, v103
	v_pk_add_f32 v[98:99], v[98:99], v[100:101]
	v_mul_f32_e32 v100, v87, v87
	v_mul_f32_e32 v102, v89, v89
	v_mul_f32_e32 v104, v84, v84
	v_mul_f32_e32 v105, v85, v85
	v_pk_fma_f32 v[100:101], v[86:87], v[86:87], v[100:101] op_sel_hi:[1,1,0]
	v_pk_fma_f32 v[102:103], v[88:89], v[88:89], v[102:103] op_sel_hi:[1,1,0]
	v_mov_b32_e32 v101, v104
	v_mov_b32_e32 v103, v105
	v_pk_add_f32 v[100:101], v[100:101], v[102:103]
	s_nop 0
	v_pk_add_f32 v[98:99], v[98:99], v[100:101]
	v_add_u32_e32 v101, 32, v166
	v_add_f32_e32 v98, v98, v99
	v_mov_b32_e32 v99, v98
	v_add_u32_e32 v102, s79, v101
	s_nop 1
	v_permlane16_swap_b32 v99, v98
	v_add_f32_e32 v98, v98, v99
	v_mov_b32_e32 v99, v98
	s_nop 1
	v_permlane32_swap_b32 v99, v98
	v_add_f32_e32 v98, v98, v99
	v_fmamk_f32 v98, v98, 0x3c800000, v196
	v_mul_f32_e32 v99, 0x4b800000, v98
	v_cmp_gt_f32_e32 vcc, s65, v98
	s_nop 1
	v_cndmask_b32_e32 v98, v98, v99, vcc
	v_rsq_f32_e32 v98, v98
	s_nop 0
	v_mul_f32_e32 v99, 0x45800000, v98
	v_cndmask_b32_e32 v98, v98, v99, vcc
	v_mul_f32_e32 v100, v167, v98
	v_ashrrev_i32_e32 v98, 6, v102
	v_ashrrev_i32_e32 v99, 31, v98
	v_lshlrev_b32_e32 v102, 6, v102
	v_pk_mul_f32 v[94:95], v[94:95], v[100:101] op_sel_hi:[1,0]
	v_pk_mul_f32 v[96:97], v[96:97], v[100:101] op_sel_hi:[1,0]
	v_pk_mul_f32 v[90:91], v[90:91], v[100:101] op_sel_hi:[1,0]
	v_pk_mul_f32 v[92:93], v[92:93], v[100:101] op_sel_hi:[1,0]
	v_lshl_add_u64 v[98:99], s[88:89], 0, v[98:99]
	v_and_b32_e32 v104, 0xfc0, v102
	v_pk_mul_f32 v[96:97], v[144:145], v[96:97]
	v_pk_mul_f32 v[94:95], v[142:143], v[94:95]
	v_pk_mul_f32 v[102:103], v[140:141], v[92:93]
	v_pk_mul_f32 v[92:93], v[138:139], v[90:91]
	v_lshlrev_b64 v[98:99], 13, v[98:99]
	v_cvt_pk_bf16_f32 v90, v94, v95
	v_cvt_pk_bf16_f32 v91, v96, v97
	v_cvt_pk_bf16_f32 v92, v92, v93
	v_cvt_pk_bf16_f32 v93, v102, v103
	s_and_b64 vcc, exec, s[10:11]
	v_lshlrev_b32_e32 v154, 1, v104
	s_cbranch_vccnz .LBB0_193
	v_ashrrev_i32_e32 v127, 31, v126
	v_lshl_add_u64 v[94:95], s[48:49], 0, v[154:155]
	v_lshl_add_u64 v[94:95], v[126:127], 1, v[94:95]
	v_lshl_add_u64 v[94:95], v[94:95], 0, v[98:99]
	s_mov_b64 s[90:91], 0
	global_store_dwordx4 v[94:95], v[90:93], off

; __device__ __forceinline__ u32x4 pack8f(const f32x4 a, const f32x4 b) { u32x4 w; w.x = cvt_pk_bf16(a[0], a[1]); w.y = cvt_pk_bf16(a[2], a[3]); w.z = cvt_pk_bf16(b[0], b[1]); w.w = cvt_pk_bf16(b[2], b[3]); return w; }
;     __device__ __forceinline__ void operator()(f32x4 (&acc)[2][2][4][2], const Unit& u, int wr, int wc, int fr, int fq) const {
;     ...
;                 for (int m = 0; m < 4; ++m) {
;                     float ss = 0.f;
; #pragma unroll
;                     for (int bj = 0; bj < 2; ++bj)
; #pragma unroll
;                         for (int n = 0; n < 2; ++n) { const f32x4 x = acc[ai][bj][m][n]; ss += (x[0] * x[0] + x[1] * x[1]) + (x[2] * x[2] + x[3] * x[3]); }
;                     ss += __shfl_xor(ss, 16); ss += __shfl_xor(ss, 32);
;                     const float sc = rsqrtf(ss * (1.f / 64.f) + EPS) * (isq ? C2 : 1.f);
;                     const int rl = rl0 + 128 * ai + 16 * m;
; #pragma unroll
;                     for (int bj = 0; bj < 2; ++bj) {
;                         const u32x4 w = pack8f(acc[ai][bj][m][0] * sc * gv[bj][0], acc[ai][bj][m][1] * sc * gv[bj][1]);
;                         if (isq) *(u32x4*)(Q + (size_t)(u.pm * 256 + rl) * AW + grp * 64 + 32 * bj + 8 * fq) = w;
;                         else *(u32x4*)(KI + kimg_off(b, grp >> 1, grp & 1, s0 + rl + NMETA, 32 * bj + 8 * fq)) = w;
;                     }
.LBB0_199:
	s_nop 1
	v_pk_mul_f32 v[82:83], v[80:81], v[80:81]
	v_pk_mul_f32 v[84:85], v[78:79], v[78:79]
	s_mov_b64 s[90:91], -1
	v_pk_mov_b32 v[86:87], v[84:85], v[82:83] op_sel:[1,0]
	v_mov_b32_e32 v85, v83
	v_pk_add_f32 v[82:83], v[86:87], v[84:85]
	v_pk_mul_f32 v[84:85], v[76:77], v[76:77]
	v_pk_mul_f32 v[86:87], v[74:75], v[74:75]
	v_pk_add_f32 v[82:83], v[82:83], v[82:83] op_sel:[0,1] op_sel_hi:[1,0]
	v_pk_mov_b32 v[88:89], v[86:87], v[84:85] op_sel:[1,0]
	v_mov_b32_e32 v87, v85
	v_pk_add_f32 v[84:85], v[88:89], v[86:87]
	v_mul_f32_e32 v86, v66, v66
	v_mul_f32_e32 v87, v67, v67
	v_pk_add_f32 v[84:85], v[84:85], v[84:85] op_sel:[0,1] op_sel_hi:[1,0]
	v_mov_b32_e32 v83, v86
	v_mov_b32_e32 v85, v87
	v_pk_add_f32 v[82:83], v[82:83], v[84:85]
	v_mul_f32_e32 v84, v71, v71
	v_mul_f32_e32 v86, v73, v73
	v_mul_f32_e32 v88, v68, v68
	v_mul_f32_e32 v89, v69, v69
	v_pk_fma_f32 v[84:85], v[70:71], v[70:71], v[84:85] op_sel_hi:[1,1,0]
	v_pk_fma_f32 v[86:87], v[72:73], v[72:73], v[86:87] op_sel_hi:[1,1,0]
	v_mov_b32_e32 v85, v88
	v_mov_b32_e32 v87, v89
	v_pk_add_f32 v[84:85], v[84:85], v[86:87]
	s_nop 0
	v_pk_add_f32 v[82:83], v[82:83], v[84:85]
	v_add_u32_e32 v85, 48, v166
	v_add_f32_e32 v82, v82, v83
	v_mov_b32_e32 v83, v82
	v_add_u32_e32 v86, s79, v85
	s_nop 1
	v_permlane16_swap_b32 v83, v82
	v_add_f32_e32 v82, v82, v83
	v_mov_b32_e32 v83, v82
	s_nop 1
	v_permlane32_swap_b32 v83, v82
	v_add_f32_e32 v82, v82, v83
	v_fmamk_f32 v82, v82, 0x3c800000, v196
	v_mul_f32_e32 v83, 0x4b800000, v82
	v_cmp_gt_f32_e32 vcc, s65, v82
	s_nop 1
	v_cndmask_b32_e32 v82, v82, v83, vcc
	v_rsq_f32_e32 v82, v82
	s_nop 0
	v_mul_f32_e32 v83, 0x45800000, v82
	v_cndmask_b32_e32 v82, v82, v83, vcc
	v_mul_f32_e32 v84, v167, v82
	v_ashrrev_i32_e32 v82, 6, v86
	v_ashrrev_i32_e32 v83, 31, v82
	v_lshlrev_b32_e32 v86, 6, v86
	v_pk_mul_f32 v[78:79], v[78:79], v[84:85] op_sel_hi:[1,0]
	v_pk_mul_f32 v[80:81], v[80:81], v[84:85] op_sel_hi:[1,0]
	v_pk_mul_f32 v[74:75], v[74:75], v[84:85] op_sel_hi:[1,0]
	v_pk_mul_f32 v[76:77], v[76:77], v[84:85] op_sel_hi:[1,0]
	v_lshl_add_u64 v[82:83], s[88:89], 0, v[82:83]
	v_and_b32_e32 v88, 0xfc0, v86
	v_pk_mul_f32 v[80:81], v[144:145], v[80:81]
	v_pk_mul_f32 v[78:79], v[142:143], v[78:79]
	v_pk_mul_f32 v[86:87], v[140:141], v[76:77]
	v_pk_mul_f32 v[76:77], v[138:139], v[74:75]
	v_lshlrev_b64 v[82:83], 13, v[82:83]
	v_cvt_pk_bf16_f32 v74, v78, v79
	v_cvt_pk_bf16_f32 v75, v80, v81
	v_cvt_pk_bf16_f32 v76, v76, v77
	v_cvt_pk_bf16_f32 v77, v86, v87
	s_and_b64 vcc, exec, s[10:11]
	v_lshlrev_b32_e32 v154, 1, v88
	s_cbranch_vccnz .LBB0_201
	v_ashrrev_i32_e32 v127, 31, v126
	v_lshl_add_u64 v[78:79], s[48:49], 0, v[154:155]
	v_lshl_add_u64 v[78:79], v[126:127], 1, v[78:79]
	v_lshl_add_u64 v[78:79], v[78:79], 0, v[82:83]
	s_mov_b64 s[90:91], 0
	global_store_dwordx4 v[78:79], v[74:77], off

; __device__ __forceinline__ u32x4 pack8f(const f32x4 a, const f32x4 b) { u32x4 w; w.x = cvt_pk_bf16(a[0], a[1]); w.y = cvt_pk_bf16(a[2], a[3]); w.z = cvt_pk_bf16(b[0], b[1]); w.w = cvt_pk_bf16(b[2], b[3]); return w; }
;     __device__ __forceinline__ void operator()(f32x4 (&acc)[2][2][4][2], const Unit& u, int wr, int wc, int fr, int fq) const {
;     ...
;                 for (int m = 0; m < 4; ++m) {
;                     float ss = 0.f;
; #pragma unroll
;                     for (int bj = 0; bj < 2; ++bj)
; #pragma unroll
;                         for (int n = 0; n < 2; ++n) { const f32x4 x = acc[ai][bj][m][n]; ss += (x[0] * x[0] + x[1] * x[1]) + (x[2] * x[2] + x[3] * x[3]); }
;                     ss += __shfl_xor(ss, 16); ss += __shfl_xor(ss, 32);
;                     const float sc = rsqrtf(ss * (1.f / 64.f) + EPS) * (isq ? C2 : 1.f);
;                     const int rl = rl0 + 128 * ai + 16 * m;
; #pragma unroll
;                     for (int bj = 0; bj < 2; ++bj) {
;                         const u32x4 w = pack8f(acc[ai][bj][m][0] * sc * gv[bj][0], acc[ai][bj][m][1] * sc * gv[bj][1]);
;                         if (isq) *(u32x4*)(Q + (size_t)(u.pm * 256 + rl) * AW + grp * 64 + 32 * bj + 8 * fq) = w;
;                         else *(u32x4*)(KI + kimg_off(b, grp >> 1, grp & 1, s0 + rl + NMETA, 32 * bj + 8 * fq)) = w;
;                     }
.LBB0_207:
	s_nop 1
	v_pk_mul_f32 v[66:67], v[64:65], v[64:65]
	v_pk_mul_f32 v[68:69], v[62:63], v[62:63]
	s_mov_b64 s[90:91], -1
	v_pk_mov_b32 v[70:71], v[68:69], v[66:67] op_sel:[1,0]
	v_mov_b32_e32 v69, v67
	v_pk_add_f32 v[66:67], v[70:71], v[68:69]
	v_pk_mul_f32 v[68:69], v[60:61], v[60:61]
	v_pk_mul_f32 v[70:71], v[58:59], v[58:59]
	v_pk_add_f32 v[66:67], v[66:67], v[66:67] op_sel:[0,1] op_sel_hi:[1,0]
	v_pk_mov_b32 v[72:73], v[70:71], v[68:69] op_sel:[1,0]
	v_mov_b32_e32 v71, v69
	v_pk_add_f32 v[68:69], v[72:73], v[70:71]
	v_mul_f32_e32 v70, v50, v50
	v_mul_f32_e32 v71, v51, v51
	v_pk_add_f32 v[68:69], v[68:69], v[68:69] op_sel:[0,1] op_sel_hi:[1,0]
	v_mov_b32_e32 v67, v70
	v_mov_b32_e32 v69, v71
	v_pk_add_f32 v[66:67], v[66:67], v[68:69]
	v_mul_f32_e32 v68, v55, v55
	v_mul_f32_e32 v70, v57, v57
	v_mul_f32_e32 v72, v52, v52
	v_mul_f32_e32 v73, v53, v53
	v_pk_fma_f32 v[68:69], v[54:55], v[54:55], v[68:69] op_sel_hi:[1,1,0]
	v_pk_fma_f32 v[70:71], v[56:57], v[56:57], v[70:71] op_sel_hi:[1,1,0]
	v_mov_b32_e32 v69, v72
	v_mov_b32_e32 v71, v73
	v_pk_add_f32 v[68:69], v[68:69], v[70:71]
	s_nop 0
	v_pk_add_f32 v[66:67], v[66:67], v[68:69]
	v_add_u32_e32 v69, 0x80, v166
	v_add_f32_e32 v66, v66, v67
	v_mov_b32_e32 v67, v66
	v_add_u32_e32 v70, s79, v69
	s_nop 1
	v_permlane16_swap_b32 v67, v66
	v_add_f32_e32 v66, v66, v67
	v_mov_b32_e32 v67, v66
	s_nop 1
	v_permlane32_swap_b32 v67, v66
	v_add_f32_e32 v66, v66, v67
	v_fmamk_f32 v66, v66, 0x3c800000, v196
	v_mul_f32_e32 v67, 0x4b800000, v66
	v_cmp_gt_f32_e32 vcc, s65, v66
	s_nop 1
	v_cndmask_b32_e32 v66, v66, v67, vcc
	v_rsq_f32_e32 v66, v66
	s_nop 0
	v_mul_f32_e32 v67, 0x45800000, v66
	v_cndmask_b32_e32 v66, v66, v67, vcc
	v_mul_f32_e32 v68, v167, v66
	v_ashrrev_i32_e32 v66, 6, v70
	v_ashrrev_i32_e32 v67, 31, v66
	v_lshlrev_b32_e32 v70, 6, v70
	v_pk_mul_f32 v[62:63], v[62:63], v[68:69] op_sel_hi:[1,0]
	v_pk_mul_f32 v[64:65], v[64:65], v[68:69] op_sel_hi:[1,0]
	v_pk_mul_f32 v[58:59], v[58:59], v[68:69] op_sel_hi:[1,0]
	v_pk_mul_f32 v[60:61], v[60:61], v[68:69] op_sel_hi:[1,0]
	v_lshl_add_u64 v[66:67], s[88:89], 0, v[66:67]
	v_and_b32_e32 v72, 0xfc0, v70
	v_pk_mul_f32 v[64:65], v[144:145], v[64:65]
	v_pk_mul_f32 v[62:63], v[142:143], v[62:63]
	v_pk_mul_f32 v[70:71], v[140:141], v[60:61]
	v_pk_mul_f32 v[60:61], v[138:139], v[58:59]
	v_lshlrev_b64 v[66:67], 13, v[66:67]
	v_cvt_pk_bf16_f32 v58, v62, v63
	v_cvt_pk_bf16_f32 v59, v64, v65
	v_cvt_pk_bf16_f32 v60, v60, v61
	v_cvt_pk_bf16_f32 v61, v70, v71
	s_and_b64 vcc, exec, s[10:11]
	v_lshlrev_b32_e32 v154, 1, v72
	s_cbranch_vccnz .LBB0_209
	v_ashrrev_i32_e32 v127, 31, v126
	v_lshl_add_u64 v[62:63], s[48:49], 0, v[154:155]
	v_lshl_add_u64 v[62:63], v[126:127], 1, v[62:63]
	v_lshl_add_u64 v[62:63], v[62:63], 0, v[66:67]
	s_mov_b64 s[90:91], 0
	global_store_dwordx4 v[62:63], v[58:61], off

; __device__ __forceinline__ u32x4 pack8f(const f32x4 a, const f32x4 b) { u32x4 w; w.x = cvt_pk_bf16(a[0], a[1]); w.y = cvt_pk_bf16(a[2], a[3]); w.z = cvt_pk_bf16(b[0], b[1]); w.w = cvt_pk_bf16(b[2], b[3]); return w; }
;     __device__ __forceinline__ void operator()(f32x4 (&acc)[2][2][4][2], const Unit& u, int wr, int wc, int fr, int fq) const {
;     ...
;                 for (int m = 0; m < 4; ++m) {
;                     float ss = 0.f;
; #pragma unroll
;                     for (int bj = 0; bj < 2; ++bj)
; #pragma unroll
;                         for (int n = 0; n < 2; ++n) { const f32x4 x = acc[ai][bj][m][n]; ss += (x[0] * x[0] + x[1] * x[1]) + (x[2] * x[2] + x[3] * x[3]); }
;                     ss += __shfl_xor(ss, 16); ss += __shfl_xor(ss, 32);
;                     const float sc = rsqrtf(ss * (1.f / 64.f) + EPS) * (isq ? C2 : 1.f);
;                     const int rl = rl0 + 128 * ai + 16 * m;
; #pragma unroll
;                     for (int bj = 0; bj < 2; ++bj) {
;                         const u32x4 w = pack8f(acc[ai][bj][m][0] * sc * gv[bj][0], acc[ai][bj][m][1] * sc * gv[bj][1]);
;                         if (isq) *(u32x4*)(Q + (size_t)(u.pm * 256 + rl) * AW + grp * 64 + 32 * bj + 8 * fq) = w;
;                         else *(u32x4*)(KI + kimg_off(b, grp >> 1, grp & 1, s0 + rl + NMETA, 32 * bj + 8 * fq)) = w;
;                     }
.LBB0_215:
	s_nop 1
	v_pk_mul_f32 v[50:51], v[48:49], v[48:49]
	v_pk_mul_f32 v[52:53], v[46:47], v[46:47]
	s_mov_b64 s[90:91], -1
	v_pk_mov_b32 v[54:55], v[52:53], v[50:51] op_sel:[1,0]
	v_mov_b32_e32 v53, v51
	v_pk_add_f32 v[50:51], v[54:55], v[52:53]
	v_pk_mul_f32 v[52:53], v[44:45], v[44:45]
	v_pk_mul_f32 v[54:55], v[42:43], v[42:43]
	v_pk_add_f32 v[50:51], v[50:51], v[50:51] op_sel:[0,1] op_sel_hi:[1,0]
	v_pk_mov_b32 v[56:57], v[54:55], v[52:53] op_sel:[1,0]
	v_mov_b32_e32 v55, v53
	v_pk_add_f32 v[52:53], v[56:57], v[54:55]
	v_mul_f32_e32 v54, v34, v34
	v_mul_f32_e32 v55, v35, v35
	v_pk_add_f32 v[52:53], v[52:53], v[52:53] op_sel:[0,1] op_sel_hi:[1,0]
	v_mov_b32_e32 v51, v54
	v_mov_b32_e32 v53, v55
	v_pk_add_f32 v[50:51], v[50:51], v[52:53]
	v_mul_f32_e32 v52, v39, v39
	v_mul_f32_e32 v54, v41, v41
	v_mul_f32_e32 v56, v36, v36
	v_mul_f32_e32 v57, v37, v37
	v_pk_fma_f32 v[52:53], v[38:39], v[38:39], v[52:53] op_sel_hi:[1,1,0]
	v_pk_fma_f32 v[54:55], v[40:41], v[40:41], v[54:55] op_sel_hi:[1,1,0]
	v_mov_b32_e32 v53, v56
	v_mov_b32_e32 v55, v57
	v_pk_add_f32 v[52:53], v[52:53], v[54:55]
	s_nop 0
	v_pk_add_f32 v[50:51], v[50:51], v[52:53]
	v_add_u32_e32 v53, 0x90, v166
	v_add_f32_e32 v50, v50, v51
	v_mov_b32_e32 v51, v50
	v_add_u32_e32 v54, s79, v53
	s_nop 1
	v_permlane16_swap_b32 v51, v50
	v_add_f32_e32 v50, v50, v51
	v_mov_b32_e32 v51, v50
	s_nop 1
	v_permlane32_swap_b32 v51, v50
	v_add_f32_e32 v50, v50, v51
	v_fmamk_f32 v50, v50, 0x3c800000, v196
	v_mul_f32_e32 v51, 0x4b800000, v50
	v_cmp_gt_f32_e32 vcc, s65, v50
	s_nop 1
	v_cndmask_b32_e32 v50, v50, v51, vcc
	v_rsq_f32_e32 v50, v50
	s_nop 0
	v_mul_f32_e32 v51, 0x45800000, v50
	v_cndmask_b32_e32 v50, v50, v51, vcc
	v_mul_f32_e32 v52, v167, v50
	v_ashrrev_i32_e32 v50, 6, v54
	v_ashrrev_i32_e32 v51, 31, v50
	v_lshlrev_b32_e32 v54, 6, v54
	v_pk_mul_f32 v[46:47], v[46:47], v[52:53] op_sel_hi:[1,0]
	v_pk_mul_f32 v[48:49], v[48:49], v[52:53] op_sel_hi:[1,0]
	v_pk_mul_f32 v[42:43], v[42:43], v[52:53] op_sel_hi:[1,0]
	v_pk_mul_f32 v[44:45], v[44:45], v[52:53] op_sel_hi:[1,0]
	v_lshl_add_u64 v[50:51], s[88:89], 0, v[50:51]
	v_and_b32_e32 v56, 0xfc0, v54
	v_pk_mul_f32 v[48:49], v[144:145], v[48:49]
	v_pk_mul_f32 v[46:47], v[142:143], v[46:47]
	v_pk_mul_f32 v[54:55], v[140:141], v[44:45]
	v_pk_mul_f32 v[44:45], v[138:139], v[42:43]
	v_lshlrev_b64 v[50:51], 13, v[50:51]
	v_cvt_pk_bf16_f32 v42, v46, v47
	v_cvt_pk_bf16_f32 v43, v48, v49
	v_cvt_pk_bf16_f32 v44, v44, v45
	v_cvt_pk_bf16_f32 v45, v54, v55
	s_and_b64 vcc, exec, s[10:11]
	v_lshlrev_b32_e32 v154, 1, v56
	s_cbranch_vccnz .LBB0_217
	v_ashrrev_i32_e32 v127, 31, v126
	v_lshl_add_u64 v[46:47], s[48:49], 0, v[154:155]
	v_lshl_add_u64 v[46:47], v[126:127], 1, v[46:47]
	v_lshl_add_u64 v[46:47], v[46:47], 0, v[50:51]
	s_mov_b64 s[90:91], 0
	global_store_dwordx4 v[46:47], v[42:45], off

; __device__ __forceinline__ u32x4 pack8f(const f32x4 a, const f32x4 b) { u32x4 w; w.x = cvt_pk_bf16(a[0], a[1]); w.y = cvt_pk_bf16(a[2], a[3]); w.z = cvt_pk_bf16(b[0], b[1]); w.w = cvt_pk_bf16(b[2], b[3]); return w; }
;     __device__ __forceinline__ void operator()(f32x4 (&acc)[2][2][4][2], const Unit& u, int wr, int wc, int fr, int fq) const {
;     ...
;                 for (int m = 0; m < 4; ++m) {
;                     float ss = 0.f;
; #pragma unroll
;                     for (int bj = 0; bj < 2; ++bj)
; #pragma unroll
;                         for (int n = 0; n < 2; ++n) { const f32x4 x = acc[ai][bj][m][n]; ss += (x[0] * x[0] + x[1] * x[1]) + (x[2] * x[2] + x[3] * x[3]); }
;                     ss += __shfl_xor(ss, 16); ss += __shfl_xor(ss, 32);
;                     const float sc = rsqrtf(ss * (1.f / 64.f) + EPS) * (isq ? C2 : 1.f);
;                     const int rl = rl0 + 128 * ai + 16 * m;
; #pragma unroll
;                     for (int bj = 0; bj < 2; ++bj) {
;                         const u32x4 w = pack8f(acc[ai][bj][m][0] * sc * gv[bj][0], acc[ai][bj][m][1] * sc * gv[bj][1]);
;                         if (isq) *(u32x4*)(Q + (size_t)(u.pm * 256 + rl) * AW + grp * 64 + 32 * bj + 8 * fq) = w;
;                         else *(u32x4*)(KI + kimg_off(b, grp >> 1, grp & 1, s0 + rl + NMETA, 32 * bj + 8 * fq)) = w;
;                     }
.LBB0_223:
	s_nop 1
	v_pk_mul_f32 v[34:35], v[32:33], v[32:33]
	v_pk_mul_f32 v[36:37], v[30:31], v[30:31]
	s_mov_b64 s[90:91], -1
	v_pk_mov_b32 v[38:39], v[36:37], v[34:35] op_sel:[1,0]
	v_mov_b32_e32 v37, v35
	v_pk_add_f32 v[34:35], v[38:39], v[36:37]
	v_pk_mul_f32 v[36:37], v[28:29], v[28:29]
	v_pk_mul_f32 v[38:39], v[26:27], v[26:27]
	v_pk_add_f32 v[34:35], v[34:35], v[34:35] op_sel:[0,1] op_sel_hi:[1,0]
	v_pk_mov_b32 v[40:41], v[38:39], v[36:37] op_sel:[1,0]
	v_mov_b32_e32 v39, v37
	v_pk_add_f32 v[36:37], v[40:41], v[38:39]
	v_mul_f32_e32 v38, v18, v18
	v_mul_f32_e32 v39, v19, v19
	v_pk_add_f32 v[36:37], v[36:37], v[36:37] op_sel:[0,1] op_sel_hi:[1,0]
	v_mov_b32_e32 v35, v38
	v_mov_b32_e32 v37, v39
	v_pk_add_f32 v[34:35], v[34:35], v[36:37]
	v_mul_f32_e32 v36, v23, v23
	v_mul_f32_e32 v38, v25, v25
	v_mul_f32_e32 v40, v20, v20
	v_mul_f32_e32 v41, v21, v21
	v_pk_fma_f32 v[36:37], v[22:23], v[22:23], v[36:37] op_sel_hi:[1,1,0]
	v_pk_fma_f32 v[38:39], v[24:25], v[24:25], v[38:39] op_sel_hi:[1,1,0]
	v_mov_b32_e32 v37, v40
	v_mov_b32_e32 v39, v41
	v_pk_add_f32 v[36:37], v[36:37], v[38:39]
	s_nop 0
	v_pk_add_f32 v[34:35], v[34:35], v[36:37]
	v_add_u32_e32 v37, 0xa0, v166
	v_add_f32_e32 v34, v34, v35
	v_mov_b32_e32 v35, v34
	v_add_u32_e32 v38, s79, v37
	s_nop 1
	v_permlane16_swap_b32 v35, v34
	v_add_f32_e32 v34, v34, v35
	v_mov_b32_e32 v35, v34
	s_nop 1
	v_permlane32_swap_b32 v35, v34
	v_add_f32_e32 v34, v34, v35
	v_fmamk_f32 v34, v34, 0x3c800000, v196
	v_mul_f32_e32 v35, 0x4b800000, v34
	v_cmp_gt_f32_e32 vcc, s65, v34
	s_nop 1
	v_cndmask_b32_e32 v34, v34, v35, vcc
	v_rsq_f32_e32 v34, v34
	s_nop 0
	v_mul_f32_e32 v35, 0x45800000, v34
	v_cndmask_b32_e32 v34, v34, v35, vcc
	v_mul_f32_e32 v36, v167, v34
	v_ashrrev_i32_e32 v34, 6, v38
	v_ashrrev_i32_e32 v35, 31, v34
	v_lshlrev_b32_e32 v38, 6, v38
	v_pk_mul_f32 v[30:31], v[30:31], v[36:37] op_sel_hi:[1,0]
	v_pk_mul_f32 v[32:33], v[32:33], v[36:37] op_sel_hi:[1,0]
	v_pk_mul_f32 v[26:27], v[26:27], v[36:37] op_sel_hi:[1,0]
	v_pk_mul_f32 v[28:29], v[28:29], v[36:37] op_sel_hi:[1,0]
	v_lshl_add_u64 v[34:35], s[88:89], 0, v[34:35]
	v_and_b32_e32 v40, 0xfc0, v38
	v_pk_mul_f32 v[32:33], v[144:145], v[32:33]
	v_pk_mul_f32 v[30:31], v[142:143], v[30:31]
	v_pk_mul_f32 v[38:39], v[140:141], v[28:29]
	v_pk_mul_f32 v[28:29], v[138:139], v[26:27]
	v_lshlrev_b64 v[34:35], 13, v[34:35]
	v_cvt_pk_bf16_f32 v26, v30, v31
	v_cvt_pk_bf16_f32 v27, v32, v33
	v_cvt_pk_bf16_f32 v28, v28, v29
	v_cvt_pk_bf16_f32 v29, v38, v39
	s_and_b64 vcc, exec, s[10:11]
	v_lshlrev_b32_e32 v154, 1, v40
	s_cbranch_vccnz .LBB0_225
	v_ashrrev_i32_e32 v127, 31, v126
	v_lshl_add_u64 v[30:31], s[48:49], 0, v[154:155]
	v_lshl_add_u64 v[30:31], v[126:127], 1, v[30:31]
	v_lshl_add_u64 v[30:31], v[30:31], 0, v[34:35]
	s_mov_b64 s[90:91], 0
	global_store_dwordx4 v[30:31], v[26:29], off

; __device__ __forceinline__ u32x4 pack8f(const f32x4 a, const f32x4 b) { u32x4 w; w.x = cvt_pk_bf16(a[0], a[1]); w.y = cvt_pk_bf16(a[2], a[3]); w.z = cvt_pk_bf16(b[0], b[1]); w.w = cvt_pk_bf16(b[2], b[3]); return w; }
;     __device__ __forceinline__ void operator()(f32x4 (&acc)[2][2][4][2], const Unit& u, int wr, int wc, int fr, int fq) const {
;     ...
;                 for (int m = 0; m < 4; ++m) {
;                     float ss = 0.f;
; #pragma unroll
;                     for (int bj = 0; bj < 2; ++bj)
; #pragma unroll
;                         for (int n = 0; n < 2; ++n) { const f32x4 x = acc[ai][bj][m][n]; ss += (x[0] * x[0] + x[1] * x[1]) + (x[2] * x[2] + x[3] * x[3]); }
;                     ss += __shfl_xor(ss, 16); ss += __shfl_xor(ss, 32);
;                     const float sc = rsqrtf(ss * (1.f / 64.f) + EPS) * (isq ? C2 : 1.f);
;                     const int rl = rl0 + 128 * ai + 16 * m;
; #pragma unroll
;                     for (int bj = 0; bj < 2; ++bj) {
;                         const u32x4 w = pack8f(acc[ai][bj][m][0] * sc * gv[bj][0], acc[ai][bj][m][1] * sc * gv[bj][1]);
;                         if (isq) *(u32x4*)(Q + (size_t)(u.pm * 256 + rl) * AW + grp * 64 + 32 * bj + 8 * fq) = w;
;                         else *(u32x4*)(KI + kimg_off(b, grp >> 1, grp & 1, s0 + rl + NMETA, 32 * bj + 8 * fq)) = w;
;                     }
.LBB0_231:
	s_nop 1
	v_pk_mul_f32 v[18:19], v[16:17], v[16:17]
	v_pk_mul_f32 v[20:21], v[14:15], v[14:15]
	s_nop 0
	v_pk_mov_b32 v[22:23], v[20:21], v[18:19] op_sel:[1,0]
	v_mov_b32_e32 v21, v19
	v_pk_add_f32 v[18:19], v[22:23], v[20:21]
	v_pk_mul_f32 v[20:21], v[12:13], v[12:13]
	v_pk_mul_f32 v[22:23], v[10:11], v[10:11]
	v_pk_add_f32 v[18:19], v[18:19], v[18:19] op_sel:[0,1] op_sel_hi:[1,0]
	v_pk_mov_b32 v[24:25], v[22:23], v[20:21] op_sel:[1,0]
	v_mov_b32_e32 v23, v21
	v_pk_add_f32 v[20:21], v[24:25], v[22:23]
	v_mul_f32_e32 v22, v2, v2
	v_mul_f32_e32 v23, v3, v3
	v_pk_add_f32 v[20:21], v[20:21], v[20:21] op_sel:[0,1] op_sel_hi:[1,0]
	v_mov_b32_e32 v19, v22
	v_mov_b32_e32 v21, v23
	v_pk_add_f32 v[18:19], v[18:19], v[20:21]
	v_mul_f32_e32 v20, v7, v7
	v_mul_f32_e32 v22, v9, v9
	v_mul_f32_e32 v24, v4, v4
	v_mul_f32_e32 v25, v5, v5
	v_pk_fma_f32 v[20:21], v[6:7], v[6:7], v[20:21] op_sel_hi:[1,1,0]
	v_pk_fma_f32 v[22:23], v[8:9], v[8:9], v[22:23] op_sel_hi:[1,1,0]
	v_mov_b32_e32 v21, v24
	v_mov_b32_e32 v23, v25
	v_pk_add_f32 v[20:21], v[20:21], v[22:23]
	s_nop 0
	v_pk_add_f32 v[18:19], v[18:19], v[20:21]
	v_add_u32_e32 v21, 0xb0, v166
	v_add_f32_e32 v18, v18, v19
	v_mov_b32_e32 v19, v18
	v_add_u32_e32 v22, s79, v21
	s_nop 1
	v_permlane16_swap_b32 v19, v18
	v_add_f32_e32 v18, v18, v19
	v_mov_b32_e32 v19, v18
	s_nop 1
	v_permlane32_swap_b32 v19, v18
	v_add_f32_e32 v18, v18, v19
	v_fmamk_f32 v18, v18, 0x3c800000, v196
	v_mul_f32_e32 v19, 0x4b800000, v18
	v_cmp_gt_f32_e32 vcc, s65, v18
	s_nop 1
	v_cndmask_b32_e32 v18, v18, v19, vcc
	v_rsq_f32_e32 v18, v18
	s_nop 0
	v_mul_f32_e32 v19, 0x45800000, v18
	v_cndmask_b32_e32 v18, v18, v19, vcc
	v_mul_f32_e32 v20, v167, v18
	v_ashrrev_i32_e32 v18, 6, v22
	v_ashrrev_i32_e32 v19, 31, v18
	v_lshlrev_b32_e32 v22, 6, v22
	v_pk_mul_f32 v[14:15], v[14:15], v[20:21] op_sel_hi:[1,0]
	v_pk_mul_f32 v[16:17], v[16:17], v[20:21] op_sel_hi:[1,0]
	v_pk_mul_f32 v[10:11], v[10:11], v[20:21] op_sel_hi:[1,0]
	v_pk_mul_f32 v[12:13], v[12:13], v[20:21] op_sel_hi:[1,0]
	v_lshl_add_u64 v[18:19], s[88:89], 0, v[18:19]
	v_and_b32_e32 v24, 0xfc0, v22
	v_pk_mul_f32 v[16:17], v[144:145], v[16:17]
	v_pk_mul_f32 v[14:15], v[142:143], v[14:15]
	v_pk_mul_f32 v[22:23], v[140:141], v[12:13]
	v_pk_mul_f32 v[12:13], v[138:139], v[10:11]
	v_lshlrev_b64 v[18:19], 13, v[18:19]
	v_cvt_pk_bf16_f32 v10, v14, v15
	v_cvt_pk_bf16_f32 v11, v16, v17
	v_cvt_pk_bf16_f32 v12, v12, v13
	v_cvt_pk_bf16_f32 v13, v22, v23
	s_mov_b64 s[88:89], -1
	s_and_b64 vcc, exec, s[10:11]
	v_lshlrev_b32_e32 v154, 1, v24
	s_cbranch_vccnz .LBB0_233
	v_ashrrev_i32_e32 v127, 31, v126
	v_lshl_add_u64 v[14:15], s[48:49], 0, v[154:155]
	v_lshl_add_u64 v[14:15], v[126:127], 1, v[14:15]
	v_lshl_add_u64 v[14:15], v[14:15], 0, v[18:19]
	s_mov_b64 s[88:89], 0
	global_store_dwordx4 v[14:15], v[10:13], off

; __device__ __forceinline__ int crow(int r, int hi) { return (r & 3) + 8 * (r >> 2) + 4 * hi; }
; __device__ __forceinline__ unsigned cvtpk(float lo, float hi) { return pg8::cvt_pk_bf16(lo, hi); }
; template <int VAR>
; __device__ __forceinline__ void dattn_block(const BlockRef& cur, const BlockRef& nxt, bool has_next, char* lds, Seam& S, const Outs& OU) {
;     ...
;     { auto rr = __builtin_amdgcn_permlane32_swap(__float_as_uint(l_reg), __float_as_uint(l_reg), false, false); l_reg = __uint_as_float(rr[0]) + __uint_as_float(rr[1]); }
;     float* li_l = (float*)(lds + L_WS) + wid * 64;
;     if (hi_t == 0) li_l[r32_t] = l_reg; asm volatile("s_waitcnt lgkmcnt(0)" ::: "memory");
;     float rli[16];
; #pragma unroll
;     for (int r = 0; r < 16; ++r) rli[r] = __builtin_amdgcn_rcpf(li_l[crow(r, hi_t)]);
;     unsigned* o0w = (unsigned*)(lds + L_O0 + wid * 8192);
;     if (cur.c == 0) {
; #pragma unroll
;         for (int d0 = 0; d0 < 4; ++d0)
; #pragma unroll
;             for (int r = 0; r < 16; r += 2) o0w[(d0 * 8 + (r >> 1)) * 64 + lane_t] = cvtpk(o[d0][r] * rli[r], o[d0][r + 1] * rli[r + 1]);
;     } else {
;         const float lam = OU.lam;
;         const int ch = lane_t & 15;
;         u32x4 gsg[8];
; #pragma unroll
;         for (int i = 0; i < 8; ++i) gsg[i] = __builtin_nontemporal_load((const u32x4*)(OU.SG + ((size_t)cur.m0 + wid * QBLK + i * 4 + (lane_t >> 4)) * AW + cur.h * 128 + ch * 8));
;         const f32x4 sg0 = *(const f32x4*)(OU.subg + ch * 8), sg1 = *(const f32x4*)(OU.subg + ch * 8 + 4);
;         unsigned short* stg = (unsigned short*)o0w;
; #pragma unroll
;         for (int d0 = 0; d0 < 4; ++d0)
; #pragma unroll
;             for (int r = 0; r < 16; r += 2) { const unsigned w = o0w[(d0 * 8 + (r >> 1)) * 64 + lane_t];
;                 o[d0][r] = __builtin_bit_cast(float, w << 16) - lam * (o[d0][r] * rli[r]);
;                 o[d0][r + 1] = __builtin_bit_cast(float, w & 0xffff0000u) - lam * (o[d0][r + 1] * rli[r + 1]); }
.LBB0_454:
	v_and_b32_e32 v4, 63, v3
	v_and_b32_e32 v129, 31, v3
	v_add_f32_e32 v3, 0, v82
	v_add_f32_e32 v3, v83, v3
	v_add_f32_e32 v3, v84, v3
	v_add_f32_e32 v3, v85, v3
	v_add_f32_e32 v3, v86, v3
	v_add_f32_e32 v3, v87, v3
	v_add_f32_e32 v3, v88, v3
	v_add_f32_e32 v3, v89, v3
	v_add_f32_e32 v3, v90, v3
	v_add_f32_e32 v3, v91, v3
	v_add_f32_e32 v3, v92, v3
	v_add_f32_e32 v3, v93, v3
	v_add_f32_e32 v3, v94, v3
	v_add_f32_e32 v3, v95, v3
	v_add_f32_e32 v3, v96, v3
	v_add_f32_e32 v3, v97, v3
	v_add_f32_e32 v3, v98, v3
	v_add_f32_e32 v3, v99, v3
	v_add_f32_e32 v3, v100, v3
	v_add_f32_e32 v3, v101, v3
	v_add_f32_e32 v3, v102, v3
	v_add_f32_e32 v3, v103, v3
	v_add_f32_e32 v3, v104, v3
	v_add_f32_e32 v3, v105, v3
	v_add_f32_e32 v3, v106, v3
	v_add_f32_e32 v3, v107, v3
	v_add_f32_e32 v3, v108, v3
	v_add_f32_e32 v3, v109, v3
	v_add_f32_e32 v3, v110, v3
	v_add_f32_e32 v3, v111, v3
	v_add_f32_e32 v3, v112, v3
	v_add_f32_e32 v3, v113, v3
	s_and_b32 s0, s82, 0x3fffffc0
	v_add_f32_e32 v3, v227, v3
	s_lshl_b32 s0, s0, 2
	v_mov_b32_e32 v5, v3
	s_add_i32 s60, s0, 0
	s_nop 0
	v_permlane32_swap_b32_e32 v3, v5
	s_add_i32 s60, s60, 0x12000
	v_cmp_gt_u32_e32 vcc, 32, v4
	s_and_saveexec_b64 s[0:1], vcc
	v_add_f32_e32 v3, v3, v5
	v_lshl_add_u32 v5, v129, 2, s60
	ds_write_b32 v5, v3
	s_or_b64 exec, exec, s[0:1]
	v_lshrrev_b32_e32 v130, 5, v4
	s_waitcnt lgkmcnt(0)
	v_lshl_add_u32 v3, v130, 4, s60
	ds_read_b128 v[8:11], v3
	ds_read_b128 v[12:15], v3 offset:32
	s_lshl_b32 s0, s81, 13
	s_add_i32 s60, s0, 0
	s_add_i32 s60, s60, 0x13800
	s_waitcnt lgkmcnt(1)
	v_rcp_f32_e32 v122, v8
	v_rcp_f32_e32 v123, v9
	v_rcp_f32_e32 v118, v10
	v_rcp_f32_e32 v119, v11
	s_waitcnt lgkmcnt(0)
	v_rcp_f32_e32 v112, v12
	ds_read_b128 v[8:11], v3 offset:64
	v_rcp_f32_e32 v113, v13
	v_rcp_f32_e32 v116, v14
	v_rcp_f32_e32 v117, v15
	ds_read_b128 v[12:15], v3 offset:96
	s_waitcnt lgkmcnt(1)
	v_rcp_f32_e32 v120, v8
	v_rcp_f32_e32 v121, v9
	v_rcp_f32_e32 v114, v10
	v_rcp_f32_e32 v115, v11
	s_waitcnt lgkmcnt(0)
	v_rcp_f32_e32 v110, v12
	v_rcp_f32_e32 v111, v13
	v_rcp_f32_e32 v16, v14
	v_rcp_f32_e32 v17, v15
	s_cmp_lg_u32 s79, 0
	v_lshl_add_u32 v3, v4, 2, s60
	s_cbranch_scc0 .LBB0_458
	s_or_b32 s0, s80, s33
	v_lshrrev_b32_e32 v128, 4, v4
	s_ashr_i32 s1, s0, 31
	v_or_b32_e32 v4, s78, v128
	v_mov_b32_e32 v5, v2
	v_and_b32_e32 v8, 0x78, v6
	v_lshl_add_u64 v[126:127], v[4:5], 0, s[0:1]
	v_lshlrev_b32_e32 v124, 1, v8
	v_mov_b32_e32 v125, v2
	v_lshl_add_u64 v[4:5], s[36:37], 0, v[124:125]
	v_lshlrev_b64 v[6:7], 10, v[126:127]
	v_lshl_add_u64 v[4:5], v[4:5], 0, v[6:7]
	v_add_co_u32_e32 v6, vcc, s59, v4
	v_lshlrev_b32_e32 v12, 2, v8
	s_nop 0
	v_addc_co_u32_e32 v7, vcc, 0, v5, vcc
	global_load_dwordx4 v[102:105], v[6:7], off offset:-4096 nt
	global_load_dwordx4 v[98:101], v[6:7], off nt
	v_add_co_u32_e32 v6, vcc, s74, v4
	v_mul_f32_e32 v140, v66, v122
	s_nop 0
	v_addc_co_u32_e32 v7, vcc, 0, v5, vcc
	global_load_dwordx4 v[94:97], v[6:7], off offset:-4096 nt
	global_load_dwordx4 v[90:93], v[6:7], off nt
	v_add_co_u32_e32 v6, vcc, s75, v4
	v_mul_f32_e32 v141, v68, v118
	s_nop 0
	v_addc_co_u32_e32 v7, vcc, 0, v5, vcc
	global_load_dwordx4 v[86:89], v[6:7], off offset:-4096 nt
	global_load_dwordx4 v[82:85], v[6:7], off nt
	v_add_co_u32_e32 v6, vcc, s76, v4
	v_mul_f32_e32 v172, v50, v122
	s_nop 0
	v_addc_co_u32_e32 v7, vcc, 0, v5, vcc
	global_load_dwordx4 v[106:109], v[4:5], off nt
	s_nop 0
	global_load_dwordx4 v[4:7], v[6:7], off nt
	ds_read2st64_b32 v[132:133], v3 offset1:1
	global_load_dwordx4 v[8:11], v12, s[42:43] offset:16
	s_nop 0
	global_load_dwordx4 v[12:15], v12, s[42:43]
	ds_read2st64_b32 v[134:135], v3 offset0:2 offset1:3
	ds_read2st64_b32 v[136:137], v3 offset0:4 offset1:5
	ds_read2st64_b32 v[138:139], v3 offset0:6 offset1:7
	v_mul_f32_e32 v173, v52, v118
	v_mul_f32_e32 v188, v34, v122
	s_waitcnt lgkmcnt(3)
	v_lshlrev_b32_e32 v131, 16, v132
	v_fma_f32 v131, -v212, v140, v131
	v_and_b32_e32 v132, 0xffff0000, v132
	v_mul_f32_e32 v140, v67, v123
	v_fma_f32 v140, -v212, v140, v132
	v_lshlrev_b32_e32 v132, 16, v133
	v_fma_f32 v141, -v212, v141, v132
	v_and_b32_e32 v132, 0xffff0000, v133
	v_mul_f32_e32 v133, v69, v119
	v_fma_f32 v142, -v212, v133, v132
	s_waitcnt lgkmcnt(2)
	v_lshlrev_b32_e32 v132, 16, v134
	v_mul_f32_e32 v133, v70, v112
	v_fma_f32 v143, -v212, v133, v132
	v_and_b32_e32 v132, 0xffff0000, v134
	v_mul_f32_e32 v133, v71, v113
	v_fma_f32 v144, -v212, v133, v132
	v_lshlrev_b32_e32 v132, 16, v135
	v_mul_f32_e32 v133, v72, v116
	v_fma_f32 v145, -v212, v133, v132
	v_and_b32_e32 v132, 0xffff0000, v135
	v_mul_f32_e32 v133, v73, v117
	v_fma_f32 v162, -v212, v133, v132
	s_waitcnt lgkmcnt(1)
	v_lshlrev_b32_e32 v132, 16, v136
	v_mul_f32_e32 v133, v74, v120
	v_fma_f32 v163, -v212, v133, v132
	v_and_b32_e32 v132, 0xffff0000, v136
	v_mul_f32_e32 v133, v75, v121
	v_fma_f32 v164, -v212, v133, v132
	v_lshlrev_b32_e32 v132, 16, v137
	v_mul_f32_e32 v133, v76, v114
	v_fma_f32 v165, -v212, v133, v132
	v_and_b32_e32 v132, 0xffff0000, v137
	v_mul_f32_e32 v133, v77, v115
	v_fma_f32 v166, -v212, v133, v132
	s_waitcnt lgkmcnt(0)
	v_lshlrev_b32_e32 v132, 16, v138
	v_mul_f32_e32 v133, v78, v110
	v_fma_f32 v167, -v212, v133, v132
	v_and_b32_e32 v132, 0xffff0000, v138
	v_mul_f32_e32 v133, v79, v111
	v_fma_f32 v168, -v212, v133, v132
	v_lshlrev_b32_e32 v132, 16, v139
	v_mul_f32_e32 v133, v80, v16
	v_fma_f32 v169, -v212, v133, v132
	ds_read2st64_b32 v[132:133], v3 offset0:8 offset1:9
	v_and_b32_e32 v134, 0xffff0000, v139
	v_mul_f32_e32 v135, v81, v17
	v_fma_f32 v170, -v212, v135, v134
	ds_read2st64_b32 v[134:135], v3 offset0:10 offset1:11
	ds_read2st64_b32 v[136:137], v3 offset0:12 offset1:13
	ds_read2st64_b32 v[138:139], v3 offset0:14 offset1:15
	s_waitcnt lgkmcnt(3)
; __device__ __forceinline__ int crow(int r, int hi) { return (r & 3) + 8 * (r >> 2) + 4 * hi; }
; __device__ __forceinline__ unsigned cvtpk(float lo, float hi) { return pg8::cvt_pk_bf16(lo, hi); }
; template <int VAR>
; __device__ __forceinline__ void dattn_block(const BlockRef& cur, const BlockRef& nxt, bool has_next, char* lds, Seam& S, const Outs& OU) {
;     ...
;             for (int r = 0; r < 16; r += 2) { const unsigned w = o0w[(d0 * 8 + (r >> 1)) * 64 + lane_t];
;                 o[d0][r] = __builtin_bit_cast(float, w << 16) - lam * (o[d0][r] * rli[r]);
;                 o[d0][r + 1] = __builtin_bit_cast(float, w & 0xffff0000u) - lam * (o[d0][r + 1] * rli[r + 1]); }
;         asm volatile("s_waitcnt lgkmcnt(0)" ::: "memory");
; #pragma unroll
;         for (int r = 0; r < 16; ++r) { const int orow = crow(r, hi_t);
; #pragma unroll
;             for (int d0 = 0; d0 < 4; ++d0) stg[orow * 128 + d0 * 32 + r32_t] = (unsigned short)(cvtpk(o[d0][r], 0.f) & 0xffffu); }
	v_lshlrev_b32_e32 v171, 16, v132
	v_fma_f32 v171, -v212, v172, v171
	v_and_b32_e32 v132, 0xffff0000, v132
	v_mul_f32_e32 v172, v51, v123
	v_fma_f32 v172, -v212, v172, v132
	v_lshlrev_b32_e32 v132, 16, v133
	v_fma_f32 v173, -v212, v173, v132
	v_and_b32_e32 v132, 0xffff0000, v133
	v_mul_f32_e32 v133, v53, v119
	v_fma_f32 v174, -v212, v133, v132
	s_waitcnt lgkmcnt(2)
	v_lshlrev_b32_e32 v132, 16, v134
	v_mul_f32_e32 v133, v54, v112
	v_fma_f32 v175, -v212, v133, v132
	v_and_b32_e32 v132, 0xffff0000, v134
	v_mul_f32_e32 v133, v55, v113
	v_fma_f32 v176, -v212, v133, v132
	v_lshlrev_b32_e32 v132, 16, v135
	v_mul_f32_e32 v133, v56, v116
	v_fma_f32 v177, -v212, v133, v132
	v_and_b32_e32 v132, 0xffff0000, v135
	v_mul_f32_e32 v133, v57, v117
	v_fma_f32 v178, -v212, v133, v132
	s_waitcnt lgkmcnt(1)
	v_lshlrev_b32_e32 v132, 16, v136
	v_mul_f32_e32 v133, v58, v120
	v_fma_f32 v179, -v212, v133, v132
	v_and_b32_e32 v132, 0xffff0000, v136
	v_mul_f32_e32 v133, v59, v121
	v_fma_f32 v180, -v212, v133, v132
	v_lshlrev_b32_e32 v132, 16, v137
	v_mul_f32_e32 v133, v60, v114
	v_fma_f32 v181, -v212, v133, v132
	v_and_b32_e32 v132, 0xffff0000, v137
	v_mul_f32_e32 v133, v61, v115
	v_fma_f32 v182, -v212, v133, v132
	s_waitcnt lgkmcnt(0)
	v_lshlrev_b32_e32 v132, 16, v138
	v_mul_f32_e32 v133, v62, v110
	v_fma_f32 v183, -v212, v133, v132
	v_and_b32_e32 v132, 0xffff0000, v138
	v_mul_f32_e32 v133, v63, v111
	v_fma_f32 v184, -v212, v133, v132
	v_lshlrev_b32_e32 v132, 16, v139
	v_mul_f32_e32 v133, v64, v16
	v_fma_f32 v185, -v212, v133, v132
	ds_read2st64_b32 v[132:133], v3 offset0:16 offset1:17
	v_and_b32_e32 v134, 0xffff0000, v139
	v_mul_f32_e32 v135, v65, v17
	v_fma_f32 v186, -v212, v135, v134
	ds_read2st64_b32 v[134:135], v3 offset0:18 offset1:19
	ds_read2st64_b32 v[136:137], v3 offset0:20 offset1:21
	ds_read2st64_b32 v[138:139], v3 offset0:22 offset1:23
	s_waitcnt lgkmcnt(3)
	v_lshlrev_b32_e32 v187, 16, v132
	v_fma_f32 v187, -v212, v188, v187
	v_and_b32_e32 v132, 0xffff0000, v132
	v_mul_f32_e32 v188, v35, v123
	v_fma_f32 v188, -v212, v188, v132
	v_lshlrev_b32_e32 v132, 16, v133
	v_mul_f32_e32 v189, v36, v118
	v_fma_f32 v189, -v212, v189, v132
	v_and_b32_e32 v132, 0xffff0000, v133
	v_mul_f32_e32 v133, v37, v119
	v_fma_f32 v190, -v212, v133, v132
	s_waitcnt lgkmcnt(2)
	v_lshlrev_b32_e32 v132, 16, v134
	v_mul_f32_e32 v133, v38, v112
	v_fma_f32 v191, -v212, v133, v132
	v_and_b32_e32 v132, 0xffff0000, v134
	v_mul_f32_e32 v133, v39, v113
	v_fma_f32 v192, -v212, v133, v132
	v_lshlrev_b32_e32 v132, 16, v135
	v_mul_f32_e32 v133, v40, v116
	v_fma_f32 v193, -v212, v133, v132
	v_and_b32_e32 v132, 0xffff0000, v135
	v_mul_f32_e32 v133, v41, v117
	v_fma_f32 v194, -v212, v133, v132
	s_waitcnt lgkmcnt(1)
	v_lshlrev_b32_e32 v132, 16, v136
	v_mul_f32_e32 v133, v42, v120
	v_fma_f32 v195, -v212, v133, v132
	v_and_b32_e32 v132, 0xffff0000, v136
	v_mul_f32_e32 v133, v43, v121
	v_fma_f32 v196, -v212, v133, v132
	v_lshlrev_b32_e32 v132, 16, v137
	v_mul_f32_e32 v133, v44, v114
	v_fma_f32 v197, -v212, v133, v132
	v_and_b32_e32 v132, 0xffff0000, v137
	v_mul_f32_e32 v133, v45, v115
	v_fma_f32 v204, -v212, v133, v132
	s_waitcnt lgkmcnt(0)
	v_lshlrev_b32_e32 v132, 16, v138
	v_mul_f32_e32 v133, v46, v110
	v_fma_f32 v206, -v212, v133, v132
	v_and_b32_e32 v132, 0xffff0000, v138
	v_mul_f32_e32 v133, v47, v111
	v_fma_f32 v207, -v212, v133, v132
	v_lshlrev_b32_e32 v132, 16, v139
	v_mul_f32_e32 v133, v48, v16
	v_fma_f32 v208, -v212, v133, v132
	ds_read2st64_b32 v[132:133], v3 offset0:24 offset1:25
	v_lshlrev_b32_e32 v130, 10, v130
	v_lshlrev_b32_e32 v129, 1, v129
	v_and_b32_e32 v134, 0xffff0000, v139
	v_mul_f32_e32 v135, v49, v17
	v_add3_u32 v129, s60, v130, v129
	v_cvt_pk_bf16_f32 v130, v131, s0
	v_fma_f32 v209, -v212, v135, v134
	ds_read2st64_b32 v[134:135], v3 offset0:26 offset1:27
	ds_read2st64_b32 v[136:137], v3 offset0:28 offset1:29
	ds_read2st64_b32 v[138:139], v3 offset0:30 offset1:31
	s_waitcnt lgkmcnt(3)
	v_lshlrev_b32_e32 v227, 16, v132
	v_mul_f32_e32 v228, v18, v122
	s_waitcnt lgkmcnt(0)
	ds_write_b16 v129, v130
	v_cvt_pk_bf16_f32 v130, v171, s0
	v_fma_f32 v227, -v212, v228, v227
	ds_write_b16 v129, v130 offset:64
	v_cvt_pk_bf16_f32 v130, v187, s0
	ds_write_b16 v129, v130 offset:128
	v_cvt_pk_bf16_f32 v130, v227, s0
	ds_write_b16 v129, v130 offset:192
	v_cvt_pk_bf16_f32 v130, v140, s0
	v_and_b32_e32 v132, 0xffff0000, v132
	v_mul_f32_e32 v228, v19, v123
	ds_write_b16 v129, v130 offset:256
	v_cvt_pk_bf16_f32 v130, v172, s0
	v_fma_f32 v132, -v212, v228, v132
	ds_write_b16 v129, v130 offset:320
	v_cvt_pk_bf16_f32 v130, v188, s0
	ds_write_b16 v129, v130 offset:384
	v_cvt_pk_bf16_f32 v130, v132, s0
	ds_write_b16 v129, v130 offset:448
	v_cvt_pk_bf16_f32 v130, v141, s0
	v_lshlrev_b32_e32 v228, 16, v133
	v_mul_f32_e32 v229, v20, v118
	ds_write_b16 v129, v130 offset:512
	v_cvt_pk_bf16_f32 v130, v173, s0
	v_fma_f32 v228, -v212, v229, v228
	ds_write_b16 v129, v130 offset:576
	v_cvt_pk_bf16_f32 v130, v189, s0
	ds_write_b16 v129, v130 offset:640
	v_cvt_pk_bf16_f32 v130, v228, s0
	ds_write_b16 v129, v130 offset:704
	v_cvt_pk_bf16_f32 v130, v142, s0
	v_and_b32_e32 v133, 0xffff0000, v133
	v_mul_f32_e32 v229, v21, v119
	ds_write_b16 v129, v130 offset:768
	v_cvt_pk_bf16_f32 v130, v174, s0
	v_fma_f32 v133, -v212, v229, v133
	ds_write_b16 v129, v130 offset:832
	v_cvt_pk_bf16_f32 v130, v190, s0
	ds_write_b16 v129, v130 offset:896
	v_cvt_pk_bf16_f32 v130, v133, s0
	ds_write_b16 v129, v130 offset:960
	v_cvt_pk_bf16_f32 v130, v143, s0
	s_waitcnt lgkmcnt(14)
; __device__ __forceinline__ int crow(int r, int hi) { return (r & 3) + 8 * (r >> 2) + 4 * hi; }
; __device__ __forceinline__ unsigned cvtpk(float lo, float hi) { return pg8::cvt_pk_bf16(lo, hi); }
; template <int VAR>
; __device__ __forceinline__ void dattn_block(const BlockRef& cur, const BlockRef& nxt, bool has_next, char* lds, Seam& S, const Outs& OU) {
;     ...
;         for (int r = 0; r < 16; ++r) { const int orow = crow(r, hi_t);
; #pragma unroll
;             for (int d0 = 0; d0 < 4; ++d0) stg[orow * 128 + d0 * 32 + r32_t] = (unsigned short)(cvtpk(o[d0][r], 0.f) & 0xffffu); }
;         asm volatile("s_waitcnt lgkmcnt(0)" ::: "memory");
;         constexpr float SC = 1.f - LAM_INIT;
; #pragma unroll
;         for (int i = 0; i < 8; ++i) { const int row = i * 4 + (lane_t >> 4);
;             const u32x4 v = *(const u32x4*)(stg + row * 128 + ch * 8);
;             float x0 = __builtin_bit_cast(float, v.x << 16), x1 = __builtin_bit_cast(float, v.x & 0xffff0000u), x2 = __builtin_bit_cast(float, v.y << 16), x3 = __builtin_bit_cast(float, v.y & 0xffff0000u);
;             float x4 = __builtin_bit_cast(float, v.z << 16), x5 = __builtin_bit_cast(float, v.z & 0xffff0000u), x6 = __builtin_bit_cast(float, v.w << 16), x7 = __builtin_bit_cast(float, v.w & 0xffff0000u);
;             float s = ((x0 * x0 + x1 * x1) + (x2 * x2 + x3 * x3)) + ((x4 * x4 + x5 * x5) + (x6 * x6 + x7 * x7));
	v_lshlrev_b32_e32 v229, 16, v134
	v_mul_f32_e32 v230, v22, v112
	ds_write_b16 v129, v130 offset:2048
	v_cvt_pk_bf16_f32 v130, v175, s0
	v_fma_f32 v229, -v212, v230, v229
	ds_write_b16 v129, v130 offset:2112
	v_cvt_pk_bf16_f32 v130, v191, s0
	ds_write_b16 v129, v130 offset:2176
	v_cvt_pk_bf16_f32 v130, v229, s0
	ds_write_b16 v129, v130 offset:2240
	v_cvt_pk_bf16_f32 v130, v144, s0
	v_and_b32_e32 v134, 0xffff0000, v134
	v_mul_f32_e32 v230, v23, v113
	ds_write_b16 v129, v130 offset:2304
	v_cvt_pk_bf16_f32 v130, v176, s0
	v_fma_f32 v134, -v212, v230, v134
	ds_write_b16 v129, v130 offset:2368
	v_cvt_pk_bf16_f32 v130, v192, s0
	ds_write_b16 v129, v130 offset:2432
	v_cvt_pk_bf16_f32 v130, v134, s0
	ds_write_b16 v129, v130 offset:2496
	v_cvt_pk_bf16_f32 v130, v145, s0
	v_lshlrev_b32_e32 v230, 16, v135
	v_mul_f32_e32 v231, v24, v116
	ds_write_b16 v129, v130 offset:2560
	v_cvt_pk_bf16_f32 v130, v177, s0
	v_fma_f32 v230, -v212, v231, v230
	ds_write_b16 v129, v130 offset:2624
	v_cvt_pk_bf16_f32 v130, v193, s0
	ds_write_b16 v129, v130 offset:2688
	v_cvt_pk_bf16_f32 v130, v230, s0
	ds_write_b16 v129, v130 offset:2752
	v_cvt_pk_bf16_f32 v130, v162, s0
	v_and_b32_e32 v135, 0xffff0000, v135
	v_mul_f32_e32 v231, v25, v117
	ds_write_b16 v129, v130 offset:2816
	v_cvt_pk_bf16_f32 v130, v178, s0
	v_fma_f32 v135, -v212, v231, v135
	ds_write_b16 v129, v130 offset:2880
	v_cvt_pk_bf16_f32 v130, v194, s0
	ds_write_b16 v129, v130 offset:2944
	v_cvt_pk_bf16_f32 v130, v135, s0
	ds_write_b16 v129, v130 offset:3008
	v_cvt_pk_bf16_f32 v130, v163, s0
	v_lshlrev_b32_e32 v231, 16, v136
	v_mul_f32_e32 v232, v26, v120
	ds_write_b16 v129, v130 offset:4096
	v_cvt_pk_bf16_f32 v130, v179, s0
	v_fma_f32 v231, -v212, v232, v231
	ds_write_b16 v129, v130 offset:4160
	v_cvt_pk_bf16_f32 v130, v195, s0
	ds_write_b16 v129, v130 offset:4224
	v_cvt_pk_bf16_f32 v130, v231, s0
	ds_write_b16 v129, v130 offset:4288
	v_cvt_pk_bf16_f32 v130, v164, s0
	v_and_b32_e32 v136, 0xffff0000, v136
	v_mul_f32_e32 v232, v27, v121
	ds_write_b16 v129, v130 offset:4352
	v_cvt_pk_bf16_f32 v130, v180, s0
	v_fma_f32 v136, -v212, v232, v136
	ds_write_b16 v129, v130 offset:4416
	v_cvt_pk_bf16_f32 v130, v196, s0
	ds_write_b16 v129, v130 offset:4480
	v_cvt_pk_bf16_f32 v130, v136, s0
	ds_write_b16 v129, v130 offset:4544
	v_cvt_pk_bf16_f32 v130, v165, s0
	v_lshlrev_b32_e32 v232, 16, v137
	v_mul_f32_e32 v233, v28, v114
	ds_write_b16 v129, v130 offset:4608
	v_cvt_pk_bf16_f32 v130, v181, s0
	v_fma_f32 v232, -v212, v233, v232
	ds_write_b16 v129, v130 offset:4672
	v_cvt_pk_bf16_f32 v130, v197, s0
	ds_write_b16 v129, v130 offset:4736
	v_cvt_pk_bf16_f32 v130, v232, s0
	ds_write_b16 v129, v130 offset:4800
	v_cvt_pk_bf16_f32 v130, v166, s0
	v_and_b32_e32 v137, 0xffff0000, v137
	v_mul_f32_e32 v233, v29, v115
	ds_write_b16 v129, v130 offset:4864
	v_cvt_pk_bf16_f32 v130, v182, s0
	v_fma_f32 v137, -v212, v233, v137
	ds_write_b16 v129, v130 offset:4928
	v_cvt_pk_bf16_f32 v130, v204, s0
	ds_write_b16 v129, v130 offset:4992
	v_cvt_pk_bf16_f32 v130, v137, s0
	ds_write_b16 v129, v130 offset:5056
	v_cvt_pk_bf16_f32 v130, v167, s0
	v_lshlrev_b32_e32 v233, 16, v138
	v_mul_f32_e32 v234, v30, v110
	ds_write_b16 v129, v130 offset:6144
	v_cvt_pk_bf16_f32 v130, v183, s0
	v_fma_f32 v233, -v212, v234, v233
	ds_write_b16 v129, v130 offset:6208
	v_cvt_pk_bf16_f32 v130, v206, s0
	ds_write_b16 v129, v130 offset:6272
	v_cvt_pk_bf16_f32 v130, v233, s0
	ds_write_b16 v129, v130 offset:6336
	v_cvt_pk_bf16_f32 v130, v168, s0
	v_and_b32_e32 v138, 0xffff0000, v138
	v_mul_f32_e32 v234, v31, v111
	ds_write_b16 v129, v130 offset:6400
	v_cvt_pk_bf16_f32 v130, v184, s0
	v_fma_f32 v138, -v212, v234, v138
	ds_write_b16 v129, v130 offset:6464
	v_cvt_pk_bf16_f32 v130, v207, s0
	ds_write_b16 v129, v130 offset:6528
	v_cvt_pk_bf16_f32 v130, v138, s0
	ds_write_b16 v129, v130 offset:6592
	v_cvt_pk_bf16_f32 v130, v169, s0
	v_lshlrev_b32_e32 v234, 16, v139
	v_mul_f32_e32 v235, v32, v16
	ds_write_b16 v129, v130 offset:6656
	v_cvt_pk_bf16_f32 v130, v185, s0
	v_fma_f32 v234, -v212, v235, v234
	ds_write_b16 v129, v130 offset:6720
	v_cvt_pk_bf16_f32 v130, v208, s0
	ds_write_b16 v129, v130 offset:6784
	v_cvt_pk_bf16_f32 v130, v234, s0
	ds_write_b16 v129, v130 offset:6848
	v_cvt_pk_bf16_f32 v130, v170, s0
	v_and_b32_e32 v139, 0xffff0000, v139
	v_mul_f32_e32 v235, v33, v17
	ds_write_b16 v129, v130 offset:6912
	v_cvt_pk_bf16_f32 v130, v186, s0
	v_fma_f32 v139, -v212, v235, v139
	ds_write_b16 v129, v130 offset:6976
	v_cvt_pk_bf16_f32 v130, v209, s0
	ds_write_b16 v129, v130 offset:7040
	v_cvt_pk_bf16_f32 v130, v139, s0
	ds_write_b16 v129, v130 offset:7104
	v_add_u32_e32 v129, s60, v124
	s_waitcnt lgkmcnt(0)
	v_lshl_add_u32 v130, v128, 8, v129
	ds_read_b128 v[130:133], v130
	v_or_b32_e32 v178, 4, v128
	v_lshl_add_u32 v134, v178, 8, v129
	ds_read_b128 v[134:137], v134
	s_waitcnt vmcnt(3)
	v_lshlrev_b32_e32 v170, 16, v106
	s_waitcnt lgkmcnt(1)
	v_lshlrev_b32_e32 v138, 16, v133
	v_and_b32_e32 v139, 0xffff0000, v133
	v_and_b32_e32 v133, 0xffff0000, v131
	v_lshlrev_b32_e32 v140, 16, v132
	v_and_b32_e32 v141, 0xffff0000, v132
	v_lshlrev_b32_e32 v132, 16, v131
	v_and_b32_e32 v143, 0xffff0000, v130
	v_mov_b32_e32 v144, v133
	v_mov_b32_e32 v145, v139
	v_lshlrev_b32_e32 v142, 16, v130
	v_mov_b32_e32 v130, v132
	v_mov_b32_e32 v131, v138
	v_pk_mul_f32 v[144:145], v[144:145], v[144:145]
	v_mov_b32_e32 v162, v143
	v_mov_b32_e32 v163, v141
	v_pk_fma_f32 v[130:131], v[130:131], v[130:131], v[144:145]
	v_mov_b32_e32 v144, v142
	v_mov_b32_e32 v145, v140
	v_pk_mul_f32 v[162:163], v[162:163], v[162:163]
	s_waitcnt lgkmcnt(0)
; __device__ __forceinline__ unsigned cvtpk(float lo, float hi) { return pg8::cvt_pk_bf16(lo, hi); }
; template <int VAR>
; __device__ __forceinline__ void dattn_block(const BlockRef& cur, const BlockRef& nxt, bool has_next, char* lds, Seam& S, const Outs& OU) {
;     ...
;         for (int i = 0; i < 8; ++i) { const int row = i * 4 + (lane_t >> 4);
;             const u32x4 v = *(const u32x4*)(stg + row * 128 + ch * 8);
;             float x0 = __builtin_bit_cast(float, v.x << 16), x1 = __builtin_bit_cast(float, v.x & 0xffff0000u), x2 = __builtin_bit_cast(float, v.y << 16), x3 = __builtin_bit_cast(float, v.y & 0xffff0000u);
;             float x4 = __builtin_bit_cast(float, v.z << 16), x5 = __builtin_bit_cast(float, v.z & 0xffff0000u), x6 = __builtin_bit_cast(float, v.w << 16), x7 = __builtin_bit_cast(float, v.w & 0xffff0000u);
;             float s = ((x0 * x0 + x1 * x1) + (x2 * x2 + x3 * x3)) + ((x4 * x4 + x5 * x5) + (x6 * x6 + x7 * x7));
;             s += __shfl_xor(s, 1); s += __shfl_xor(s, 2); s += __shfl_xor(s, 4); s += __shfl_xor(s, 8);
;             const float rn = rsqrtf(s * (1.f / 128.f) + EPS) * SC;
;             const u32x4 g = gsg[i];
;             u32x4 w;
;             w.x = cvtpk(x0 * rn * __builtin_bit_cast(float, g.x << 16) * sg0[0], x1 * rn * __builtin_bit_cast(float, g.x & 0xffff0000u) * sg0[1]);
;             w.y = cvtpk(x2 * rn * __builtin_bit_cast(float, g.y << 16) * sg0[2], x3 * rn * __builtin_bit_cast(float, g.y & 0xffff0000u) * sg0[3]);
;             w.z = cvtpk(x4 * rn * __builtin_bit_cast(float, g.z << 16) * sg1[0], x5 * rn * __builtin_bit_cast(float, g.z & 0xffff0000u) * sg1[1]);
;             w.w = cvtpk(x6 * rn * __builtin_bit_cast(float, g.w << 16) * sg1[2], x7 * rn * __builtin_bit_cast(float, g.w & 0xffff0000u) * sg1[3]);
;             *(u32x4*)(OU.BR + ((size_t)cur.m0 + wid * QBLK + row) * 1024 + cur.h * 128 + ch * 8) = w; }
	v_and_b32_e32 v165, 0xffff0000, v134
	v_pk_fma_f32 v[144:145], v[144:145], v[144:145], v[162:163]
	v_lshlrev_b32_e32 v162, 16, v136
	v_pk_add_f32 v[130:131], v[144:145], v[130:131]
	v_lshlrev_b32_e32 v144, 16, v137
	v_and_b32_e32 v145, 0xffff0000, v137
	v_and_b32_e32 v137, 0xffff0000, v135
	v_and_b32_e32 v163, 0xffff0000, v136
	v_lshlrev_b32_e32 v136, 16, v135
	v_mov_b32_e32 v166, v137
	v_mov_b32_e32 v167, v145
	v_lshlrev_b32_e32 v164, 16, v134
	v_mov_b32_e32 v134, v136
	v_mov_b32_e32 v135, v144
	v_pk_mul_f32 v[166:167], v[166:167], v[166:167]
	v_mov_b32_e32 v168, v165
	v_mov_b32_e32 v169, v163
	v_pk_fma_f32 v[134:135], v[134:135], v[134:135], v[166:167]
	v_mov_b32_e32 v166, v164
	v_mov_b32_e32 v167, v162
	v_pk_mul_f32 v[168:169], v[168:169], v[168:169]
	v_and_b32_e32 v171, 0xffff0000, v106
	v_pk_fma_f32 v[166:167], v[166:167], v[166:167], v[168:169]
	v_lshlrev_b32_e32 v168, 16, v107
	v_pk_add_f32 v[134:135], v[166:167], v[134:135]
	v_mov_b32_e32 v167, v130
	v_mov_b32_e32 v166, v134
	v_mov_b32_e32 v130, v135
	v_pk_add_f32 v[130:131], v[166:167], v[130:131]
	v_and_b32_e32 v169, 0xffff0000, v107
	v_lshlrev_b32_e32 v176, 16, v102
	v_and_b32_e32 v177, 0xffff0000, v102
	v_lshlrev_b32_e32 v166, 16, v108
	v_add_f32_dpp v130, v130, v130 quad_perm:[1,0,3,2] row_mask:0xf bank_mask:0xf
	v_add_f32_dpp v131, v131, v131 quad_perm:[1,0,3,2] row_mask:0xf bank_mask:0xf
	v_and_b32_e32 v167, 0xffff0000, v108
	v_lshlrev_b32_e32 v108, 16, v109
	v_and_b32_e32 v109, 0xffff0000, v109
	v_lshlrev_b32_e32 v172, 16, v103
	v_add_f32_dpp v106, v130, v130 quad_perm:[2,3,0,1] row_mask:0xf bank_mask:0xf
	v_add_f32_dpp v107, v131, v131 quad_perm:[2,3,0,1] row_mask:0xf bank_mask:0xf
	v_lshlrev_b32_e32 v134, 16, v104
	v_and_b32_e32 v135, 0xffff0000, v104
	v_and_b32_e32 v173, 0xffff0000, v103
	v_lshlrev_b64 v[126:127], 11, v[126:127]
	v_add_f32_dpp v106, v106, v106 row_half_mirror row_mask:0xf bank_mask:0xf
	v_add_f32_dpp v107, v107, v107 row_half_mirror row_mask:0xf bank_mask:0xf
	v_lshl_add_u64 v[126:127], s[38:39], 0, v[126:127]
	v_lshl_add_u64 v[126:127], v[126:127], 0, v[124:125]
	v_add_f32_dpp v130, v106, v106 row_mirror row_mask:0xf bank_mask:0xf
	v_add_f32_dpp v131, v107, v107 row_mirror row_mask:0xf bank_mask:0xf
	v_mov_b64_e32 v[106:107], s[48:49]
	v_pk_fma_f32 v[174:175], v[130:131], s[46:47], v[106:107] op_sel_hi:[1,0,0]
	s_nop 0
	v_mul_f32_e32 v104, 0x4b800000, v175
	v_cmp_gt_f32_e32 vcc, s77, v175
	s_nop 1
	v_cndmask_b32_e32 v104, v175, v104, vcc
	v_rsq_f32_e32 v104, v104
	s_nop 0
	v_mul_f32_e32 v102, 0x45800000, v104
	v_cndmask_b32_e32 v102, v104, v102, vcc
	v_mul_f32_e32 v102, 0x3f4ccccd, v102
	v_pk_mul_f32 v[130:131], v[102:103], v[142:143] op_sel_hi:[0,1]
	v_pk_mul_f32 v[132:133], v[102:103], v[132:133] op_sel_hi:[0,1]
	v_mul_f32_e32 v104, 0x4b800000, v174
	v_cmp_gt_f32_e32 vcc, s77, v174
	v_pk_mul_f32 v[130:131], v[130:131], v[170:171]
	v_pk_mul_f32 v[132:133], v[132:133], v[168:169]
	v_cndmask_b32_e32 v104, v174, v104, vcc
	s_waitcnt vmcnt(0)
	v_pk_mul_f32 v[130:131], v[12:13], v[130:131]
	v_pk_mul_f32 v[132:133], v[14:15], v[132:133]
	v_rsq_f32_e32 v104, v104
	v_cvt_pk_bf16_f32 v130, v130, v131
	v_cvt_pk_bf16_f32 v131, v132, v133
	v_pk_mul_f32 v[132:133], v[102:103], v[140:141] op_sel_hi:[0,1]
	v_pk_mul_f32 v[102:103], v[102:103], v[138:139] op_sel_hi:[0,1]
	v_pk_mul_f32 v[132:133], v[132:133], v[166:167]
	v_pk_mul_f32 v[102:103], v[102:103], v[108:109]
	v_pk_mul_f32 v[132:133], v[8:9], v[132:133]
	v_pk_mul_f32 v[102:103], v[10:11], v[102:103]
	v_cvt_pk_bf16_f32 v132, v132, v133
	v_cvt_pk_bf16_f32 v133, v102, v103
	v_mul_f32_e32 v102, 0x45800000, v104
	v_cndmask_b32_e32 v102, v104, v102, vcc
	v_mul_f32_e32 v108, 0x3f4ccccd, v102
	global_store_dwordx4 v[126:127], v[130:133], off
	v_pk_mul_f32 v[102:103], v[108:109], v[164:165] op_sel_hi:[0,1]
	v_pk_mul_f32 v[126:127], v[108:109], v[136:137] op_sel_hi:[0,1]
	v_pk_mul_f32 v[102:103], v[102:103], v[176:177]
	v_pk_mul_f32 v[126:127], v[126:127], v[172:173]
	v_pk_mul_f32 v[102:103], v[12:13], v[102:103]
	v_pk_mul_f32 v[126:127], v[14:15], v[126:127]
	v_cvt_pk_bf16_f32 v102, v102, v103
	v_cvt_pk_bf16_f32 v103, v126, v127
	v_pk_mul_f32 v[126:127], v[108:109], v[162:163] op_sel_hi:[0,1]
	v_pk_mul_f32 v[126:127], v[126:127], v[134:135]
	v_pk_mul_f32 v[108:109], v[108:109], v[144:145] op_sel_hi:[0,1]
	v_pk_mul_f32 v[126:127], v[8:9], v[126:127]
	v_or_b32_e32 v166, 8, v128
	v_cvt_pk_bf16_f32 v104, v126, v127
	v_lshlrev_b32_e32 v126, 16, v105
	v_and_b32_e32 v127, 0xffff0000, v105
	v_pk_mul_f32 v[108:109], v[108:109], v[126:127]
	v_lshl_add_u32 v126, v166, 8, v129
	v_pk_mul_f32 v[108:109], v[10:11], v[108:109]
	ds_read_b128 v[130:133], v126
	v_cvt_pk_bf16_f32 v105, v108, v109
	v_or_b32_e32 v108, s78, v178
	v_mov_b32_e32 v109, v2
	v_lshl_add_u64 v[108:109], v[108:109], 0, s[0:1]
	v_lshlrev_b64 v[108:109], 11, v[108:109]
	v_lshl_add_u64 v[108:109], s[38:39], 0, v[108:109]
	v_lshl_add_u64 v[108:109], v[108:109], 0, v[124:125]
	v_or_b32_e32 v172, 12, v128
	global_store_dwordx4 v[108:109], v[102:105], off
	v_lshlrev_b32_e32 v164, 16, v101
	v_and_b32_e32 v165, 0xffff0000, v101
	v_lshl_add_u32 v102, v172, 8, v129
	ds_read_b128 v[102:105], v102
	s_waitcnt lgkmcnt(1)
	v_and_b32_e32 v109, 0xffff0000, v133
	v_and_b32_e32 v135, 0xffff0000, v131
	v_lshlrev_b32_e32 v108, 16, v133
	v_and_b32_e32 v127, 0xffff0000, v132
	v_lshlrev_b32_e32 v134, 16, v131
	v_and_b32_e32 v137, 0xffff0000, v130
	v_mov_b32_e32 v138, v135
	v_mov_b32_e32 v139, v109
	v_lshlrev_b32_e32 v126, 16, v132
	v_lshlrev_b32_e32 v136, 16, v130
	v_mov_b32_e32 v130, v134
	v_mov_b32_e32 v131, v108
	v_pk_mul_f32 v[138:139], v[138:139], v[138:139]
	v_mov_b32_e32 v140, v137
	v_mov_b32_e32 v141, v127
	v_pk_fma_f32 v[130:131], v[130:131], v[130:131], v[138:139]
	v_mov_b32_e32 v138, v136
	v_mov_b32_e32 v139, v126
	v_pk_mul_f32 v[140:141], v[140:141], v[140:141]
	s_waitcnt lgkmcnt(0)
; __device__ __forceinline__ unsigned cvtpk(float lo, float hi) { return pg8::cvt_pk_bf16(lo, hi); }
; template <int VAR>
; __device__ __forceinline__ void dattn_block(const BlockRef& cur, const BlockRef& nxt, bool has_next, char* lds, Seam& S, const Outs& OU) {
;     ...
;         for (int i = 0; i < 8; ++i) { const int row = i * 4 + (lane_t >> 4);
;             const u32x4 v = *(const u32x4*)(stg + row * 128 + ch * 8);
;             float x0 = __builtin_bit_cast(float, v.x << 16), x1 = __builtin_bit_cast(float, v.x & 0xffff0000u), x2 = __builtin_bit_cast(float, v.y << 16), x3 = __builtin_bit_cast(float, v.y & 0xffff0000u);
;             float x4 = __builtin_bit_cast(float, v.z << 16), x5 = __builtin_bit_cast(float, v.z & 0xffff0000u), x6 = __builtin_bit_cast(float, v.w << 16), x7 = __builtin_bit_cast(float, v.w & 0xffff0000u);
;             float s = ((x0 * x0 + x1 * x1) + (x2 * x2 + x3 * x3)) + ((x4 * x4 + x5 * x5) + (x6 * x6 + x7 * x7));
;             s += __shfl_xor(s, 1); s += __shfl_xor(s, 2); s += __shfl_xor(s, 4); s += __shfl_xor(s, 8);
;             const float rn = rsqrtf(s * (1.f / 128.f) + EPS) * SC;
;             const u32x4 g = gsg[i];
;             u32x4 w;
;             w.x = cvtpk(x0 * rn * __builtin_bit_cast(float, g.x << 16) * sg0[0], x1 * rn * __builtin_bit_cast(float, g.x & 0xffff0000u) * sg0[1]);
;             w.y = cvtpk(x2 * rn * __builtin_bit_cast(float, g.y << 16) * sg0[2], x3 * rn * __builtin_bit_cast(float, g.y & 0xffff0000u) * sg0[3]);
;             w.z = cvtpk(x4 * rn * __builtin_bit_cast(float, g.z << 16) * sg1[0], x5 * rn * __builtin_bit_cast(float, g.z & 0xffff0000u) * sg1[1]);
;             w.w = cvtpk(x6 * rn * __builtin_bit_cast(float, g.w << 16) * sg1[2], x7 * rn * __builtin_bit_cast(float, g.w & 0xffff0000u) * sg1[3]);
;             *(u32x4*)(OU.BR + ((size_t)cur.m0 + wid * QBLK + row) * 1024 + cur.h * 128 + ch * 8) = w; }
	v_and_b32_e32 v143, 0xffff0000, v102
	v_pk_fma_f32 v[138:139], v[138:139], v[138:139], v[140:141]
	v_lshlrev_b32_e32 v140, 16, v104
	v_pk_add_f32 v[130:131], v[138:139], v[130:131]
	v_lshlrev_b32_e32 v138, 16, v105
	v_and_b32_e32 v139, 0xffff0000, v105
	v_and_b32_e32 v105, 0xffff0000, v103
	v_and_b32_e32 v141, 0xffff0000, v104
	v_lshlrev_b32_e32 v104, 16, v103
	v_mov_b32_e32 v144, v105
	v_mov_b32_e32 v145, v139
	v_lshlrev_b32_e32 v142, 16, v102
	v_mov_b32_e32 v102, v104
	v_mov_b32_e32 v103, v138
	v_pk_mul_f32 v[144:145], v[144:145], v[144:145]
	v_mov_b32_e32 v162, v143
	v_mov_b32_e32 v163, v141
	v_pk_fma_f32 v[102:103], v[102:103], v[102:103], v[144:145]
	v_mov_b32_e32 v144, v142
	v_mov_b32_e32 v145, v140
	v_pk_mul_f32 v[162:163], v[162:163], v[162:163]
	v_lshlrev_b32_e32 v132, 16, v100
	v_pk_fma_f32 v[144:145], v[144:145], v[144:145], v[162:163]
	v_and_b32_e32 v133, 0xffff0000, v100
	v_pk_add_f32 v[102:103], v[144:145], v[102:103]
	v_mov_b32_e32 v145, v130
	v_mov_b32_e32 v144, v102
	v_mov_b32_e32 v130, v103
	v_pk_add_f32 v[102:103], v[144:145], v[130:131]
	v_lshlrev_b32_e32 v144, 16, v99
	v_and_b32_e32 v145, 0xffff0000, v99
	v_lshlrev_b32_e32 v162, 16, v98
	v_and_b32_e32 v163, 0xffff0000, v98
	v_add_f32_dpp v102, v102, v102 quad_perm:[1,0,3,2] row_mask:0xf bank_mask:0xf
	v_add_f32_dpp v103, v103, v103 quad_perm:[1,0,3,2] row_mask:0xf bank_mask:0xf
	v_or_b32_e32 v98, s78, v166
	v_mov_b32_e32 v99, v2
	v_lshl_add_u64 v[98:99], v[98:99], 0, s[0:1]
	v_lshlrev_b64 v[98:99], 11, v[98:99]
	v_add_f32_dpp v100, v102, v102 quad_perm:[2,3,0,1] row_mask:0xf bank_mask:0xf
	v_add_f32_dpp v101, v103, v103 quad_perm:[2,3,0,1] row_mask:0xf bank_mask:0xf
	v_lshl_add_u64 v[98:99], s[38:39], 0, v[98:99]
	v_lshl_add_u64 v[130:131], v[98:99], 0, v[124:125]
	v_lshlrev_b32_e32 v166, 16, v96
	v_and_b32_e32 v167, 0xffff0000, v96
	v_add_f32_dpp v100, v100, v100 row_half_mirror row_mask:0xf bank_mask:0xf
	v_add_f32_dpp v101, v101, v101 row_half_mirror row_mask:0xf bank_mask:0xf
	v_lshlrev_b32_e32 v170, 16, v94
	v_and_b32_e32 v171, 0xffff0000, v94
	v_lshlrev_b32_e32 v168, 16, v95
	v_and_b32_e32 v169, 0xffff0000, v95
	v_add_f32_dpp v98, v100, v100 row_mirror row_mask:0xf bank_mask:0xf
	v_add_f32_dpp v99, v101, v101 row_mirror row_mask:0xf bank_mask:0xf
	s_nop 0
	v_pk_fma_f32 v[102:103], v[98:99], s[46:47], v[106:107] op_sel_hi:[1,0,0]
	s_nop 0
	v_mul_f32_e32 v96, 0x4b800000, v103
	v_cmp_gt_f32_e32 vcc, s77, v103
	s_nop 1
	v_cndmask_b32_e32 v96, v103, v96, vcc
	v_rsq_f32_e32 v96, v96
	s_nop 0
	v_mul_f32_e32 v94, 0x45800000, v96
	v_cndmask_b32_e32 v94, v96, v94, vcc
	v_mul_f32_e32 v94, 0x3f4ccccd, v94
	v_pk_mul_f32 v[98:99], v[94:95], v[136:137] op_sel_hi:[0,1]
	v_pk_mul_f32 v[100:101], v[94:95], v[134:135] op_sel_hi:[0,1]
	v_mul_f32_e32 v96, 0x4b800000, v102
	v_cmp_gt_f32_e32 vcc, s77, v102
	v_pk_mul_f32 v[98:99], v[98:99], v[162:163]
	v_pk_mul_f32 v[100:101], v[100:101], v[144:145]
	v_cndmask_b32_e32 v96, v102, v96, vcc
	v_pk_mul_f32 v[98:99], v[12:13], v[98:99]
	v_pk_mul_f32 v[100:101], v[14:15], v[100:101]
	v_rsq_f32_e32 v96, v96
	v_cvt_pk_bf16_f32 v98, v98, v99
	v_cvt_pk_bf16_f32 v99, v100, v101
	v_pk_mul_f32 v[100:101], v[94:95], v[126:127] op_sel_hi:[0,1]
	v_pk_mul_f32 v[94:95], v[94:95], v[108:109] op_sel_hi:[0,1]
	v_pk_mul_f32 v[100:101], v[100:101], v[132:133]
	v_pk_mul_f32 v[94:95], v[94:95], v[164:165]
	v_pk_mul_f32 v[100:101], v[8:9], v[100:101]
	v_pk_mul_f32 v[94:95], v[10:11], v[94:95]
	v_cvt_pk_bf16_f32 v100, v100, v101
	v_cvt_pk_bf16_f32 v101, v94, v95
	v_mul_f32_e32 v94, 0x45800000, v96
	v_cndmask_b32_e32 v94, v96, v94, vcc
	global_store_dwordx4 v[130:131], v[98:101], off
	v_or_b32_e32 v164, 20, v128
	v_lshlrev_b32_e32 v162, 16, v86
	v_mul_f32_e32 v98, 0x3f4ccccd, v94
	v_pk_mul_f32 v[94:95], v[98:99], v[142:143] op_sel_hi:[0,1]
	v_pk_mul_f32 v[100:101], v[98:99], v[104:105] op_sel_hi:[0,1]
	v_pk_mul_f32 v[94:95], v[94:95], v[170:171]
	v_pk_mul_f32 v[100:101], v[100:101], v[168:169]
	v_pk_mul_f32 v[94:95], v[12:13], v[94:95]
	v_pk_mul_f32 v[100:101], v[14:15], v[100:101]
	v_cvt_pk_bf16_f32 v94, v94, v95
	v_cvt_pk_bf16_f32 v95, v100, v101
	v_pk_mul_f32 v[100:101], v[98:99], v[140:141] op_sel_hi:[0,1]
	v_pk_mul_f32 v[100:101], v[100:101], v[166:167]
	v_pk_mul_f32 v[98:99], v[98:99], v[138:139] op_sel_hi:[0,1]
	v_pk_mul_f32 v[100:101], v[8:9], v[100:101]
	v_or_b32_e32 v142, 16, v128
	v_cvt_pk_bf16_f32 v96, v100, v101
	v_lshlrev_b32_e32 v100, 16, v97
	v_and_b32_e32 v101, 0xffff0000, v97
	v_pk_mul_f32 v[98:99], v[98:99], v[100:101]
	v_lshlrev_b32_e32 v140, 16, v93
	v_pk_mul_f32 v[98:99], v[10:11], v[98:99]
	v_and_b32_e32 v141, 0xffff0000, v93
	v_cvt_pk_bf16_f32 v97, v98, v99
	v_or_b32_e32 v98, s78, v172
	v_mov_b32_e32 v99, v2
	v_lshl_add_u64 v[98:99], v[98:99], 0, s[0:1]
	v_lshlrev_b64 v[98:99], 11, v[98:99]
	v_lshl_add_u64 v[98:99], s[38:39], 0, v[98:99]
	v_lshl_add_u64 v[102:103], v[98:99], 0, v[124:125]
	v_lshl_add_u32 v98, v142, 8, v129
	ds_read_b128 v[98:101], v98
	global_store_dwordx4 v[102:103], v[94:97], off
	v_and_b32_e32 v143, 0xffff0000, v88
	v_and_b32_e32 v163, 0xffff0000, v86
	v_lshl_add_u32 v94, v164, 8, v129
	ds_read_b128 v[94:97], v94
	s_waitcnt lgkmcnt(1)
	v_and_b32_e32 v103, 0xffff0000, v101
	v_and_b32_e32 v109, 0xffff0000, v99
	v_lshlrev_b32_e32 v102, 16, v101
	v_and_b32_e32 v105, 0xffff0000, v100
	v_lshlrev_b32_e32 v108, 16, v99
	v_and_b32_e32 v127, 0xffff0000, v98
	v_mov_b32_e32 v130, v109
	v_mov_b32_e32 v131, v103
	v_lshlrev_b32_e32 v104, 16, v100
	v_lshlrev_b32_e32 v126, 16, v98
	v_mov_b32_e32 v98, v108
	v_mov_b32_e32 v99, v102
	v_pk_mul_f32 v[130:131], v[130:131], v[130:131]
	v_mov_b32_e32 v132, v127
	v_mov_b32_e32 v133, v105
	v_pk_fma_f32 v[98:99], v[98:99], v[98:99], v[130:131]
	v_mov_b32_e32 v130, v126
	v_mov_b32_e32 v131, v104
	v_pk_mul_f32 v[132:133], v[132:133], v[132:133]
	s_waitcnt lgkmcnt(0)
; __device__ __forceinline__ unsigned cvtpk(float lo, float hi) { return pg8::cvt_pk_bf16(lo, hi); }
; template <int VAR>
; __device__ __forceinline__ void dattn_block(const BlockRef& cur, const BlockRef& nxt, bool has_next, char* lds, Seam& S, const Outs& OU) {
;     ...
;         for (int i = 0; i < 8; ++i) { const int row = i * 4 + (lane_t >> 4);
;             const u32x4 v = *(const u32x4*)(stg + row * 128 + ch * 8);
;             float x0 = __builtin_bit_cast(float, v.x << 16), x1 = __builtin_bit_cast(float, v.x & 0xffff0000u), x2 = __builtin_bit_cast(float, v.y << 16), x3 = __builtin_bit_cast(float, v.y & 0xffff0000u);
;             float x4 = __builtin_bit_cast(float, v.z << 16), x5 = __builtin_bit_cast(float, v.z & 0xffff0000u), x6 = __builtin_bit_cast(float, v.w << 16), x7 = __builtin_bit_cast(float, v.w & 0xffff0000u);
;             float s = ((x0 * x0 + x1 * x1) + (x2 * x2 + x3 * x3)) + ((x4 * x4 + x5 * x5) + (x6 * x6 + x7 * x7));
;             s += __shfl_xor(s, 1); s += __shfl_xor(s, 2); s += __shfl_xor(s, 4); s += __shfl_xor(s, 8);
;             const float rn = rsqrtf(s * (1.f / 128.f) + EPS) * SC;
;             const u32x4 g = gsg[i];
;             u32x4 w;
;             w.x = cvtpk(x0 * rn * __builtin_bit_cast(float, g.x << 16) * sg0[0], x1 * rn * __builtin_bit_cast(float, g.x & 0xffff0000u) * sg0[1]);
;             w.y = cvtpk(x2 * rn * __builtin_bit_cast(float, g.y << 16) * sg0[2], x3 * rn * __builtin_bit_cast(float, g.y & 0xffff0000u) * sg0[3]);
;             w.z = cvtpk(x4 * rn * __builtin_bit_cast(float, g.z << 16) * sg1[0], x5 * rn * __builtin_bit_cast(float, g.z & 0xffff0000u) * sg1[1]);
;             w.w = cvtpk(x6 * rn * __builtin_bit_cast(float, g.w << 16) * sg1[2], x7 * rn * __builtin_bit_cast(float, g.w & 0xffff0000u) * sg1[3]);
;             *(u32x4*)(OU.BR + ((size_t)cur.m0 + wid * QBLK + row) * 1024 + cur.h * 128 + ch * 8) = w; }
	v_and_b32_e32 v135, 0xffff0000, v94
	v_pk_fma_f32 v[130:131], v[130:131], v[130:131], v[132:133]
	v_lshlrev_b32_e32 v132, 16, v96
	v_pk_add_f32 v[98:99], v[130:131], v[98:99]
	v_lshlrev_b32_e32 v130, 16, v97
	v_and_b32_e32 v131, 0xffff0000, v97
	v_and_b32_e32 v97, 0xffff0000, v95
	v_and_b32_e32 v133, 0xffff0000, v96
	v_lshlrev_b32_e32 v96, 16, v95
	v_mov_b32_e32 v136, v97
	v_mov_b32_e32 v137, v131
	v_lshlrev_b32_e32 v134, 16, v94
	v_mov_b32_e32 v94, v96
	v_mov_b32_e32 v95, v130
	v_pk_mul_f32 v[136:137], v[136:137], v[136:137]
	v_mov_b32_e32 v138, v135
	v_mov_b32_e32 v139, v133
	v_pk_fma_f32 v[94:95], v[94:95], v[94:95], v[136:137]
	v_mov_b32_e32 v136, v134
	v_mov_b32_e32 v137, v132
	v_pk_mul_f32 v[138:139], v[138:139], v[138:139]
	v_lshlrev_b32_e32 v100, 16, v92
	v_pk_fma_f32 v[136:137], v[136:137], v[136:137], v[138:139]
	v_and_b32_e32 v101, 0xffff0000, v92
	v_pk_add_f32 v[94:95], v[136:137], v[94:95]
	v_mov_b32_e32 v137, v98
	v_mov_b32_e32 v136, v94
	v_mov_b32_e32 v98, v95
	v_pk_add_f32 v[94:95], v[136:137], v[98:99]
	v_lshlrev_b32_e32 v136, 16, v91
	v_and_b32_e32 v137, 0xffff0000, v91
	v_lshlrev_b32_e32 v138, 16, v90
	v_and_b32_e32 v139, 0xffff0000, v90
	v_add_f32_dpp v94, v94, v94 quad_perm:[1,0,3,2] row_mask:0xf bank_mask:0xf
	v_add_f32_dpp v95, v95, v95 quad_perm:[1,0,3,2] row_mask:0xf bank_mask:0xf
	v_or_b32_e32 v90, s78, v142
	v_mov_b32_e32 v91, v2
	v_lshl_add_u64 v[90:91], v[90:91], 0, s[0:1]
	v_lshlrev_b64 v[90:91], 11, v[90:91]
	v_add_f32_dpp v92, v94, v94 quad_perm:[2,3,0,1] row_mask:0xf bank_mask:0xf
	v_add_f32_dpp v93, v95, v95 quad_perm:[2,3,0,1] row_mask:0xf bank_mask:0xf
	v_lshl_add_u64 v[90:91], s[38:39], 0, v[90:91]
	v_lshl_add_u64 v[98:99], v[90:91], 0, v[124:125]
	v_lshlrev_b32_e32 v142, 16, v88
	v_lshlrev_b32_e32 v144, 16, v87
	v_add_f32_dpp v92, v92, v92 row_half_mirror row_mask:0xf bank_mask:0xf
	v_add_f32_dpp v93, v93, v93 row_half_mirror row_mask:0xf bank_mask:0xf
	v_and_b32_e32 v145, 0xffff0000, v87
	s_nop 1
	v_add_f32_dpp v90, v92, v92 row_mirror row_mask:0xf bank_mask:0xf
	v_add_f32_dpp v91, v93, v93 row_mirror row_mask:0xf bank_mask:0xf
	s_nop 0
	v_pk_fma_f32 v[94:95], v[90:91], s[46:47], v[106:107] op_sel_hi:[1,0,0]
	s_nop 0
	v_mul_f32_e32 v88, 0x4b800000, v95
	v_cmp_gt_f32_e32 vcc, s77, v95
	s_nop 1
	v_cndmask_b32_e32 v88, v95, v88, vcc
	v_rsq_f32_e32 v88, v88
	s_nop 0
	v_mul_f32_e32 v86, 0x45800000, v88
	v_cndmask_b32_e32 v86, v88, v86, vcc
	v_mul_f32_e32 v86, 0x3f4ccccd, v86
	v_pk_mul_f32 v[90:91], v[86:87], v[126:127] op_sel_hi:[0,1]
	v_pk_mul_f32 v[92:93], v[86:87], v[108:109] op_sel_hi:[0,1]
	v_mul_f32_e32 v88, 0x4b800000, v94
	v_cmp_gt_f32_e32 vcc, s77, v94
	v_pk_mul_f32 v[90:91], v[90:91], v[138:139]
	v_pk_mul_f32 v[92:93], v[92:93], v[136:137]
	v_cndmask_b32_e32 v88, v94, v88, vcc
	v_pk_mul_f32 v[90:91], v[12:13], v[90:91]
	v_pk_mul_f32 v[92:93], v[14:15], v[92:93]
	v_rsq_f32_e32 v88, v88
	v_cvt_pk_bf16_f32 v90, v90, v91
	v_cvt_pk_bf16_f32 v91, v92, v93
	v_pk_mul_f32 v[92:93], v[86:87], v[104:105] op_sel_hi:[0,1]
	v_pk_mul_f32 v[86:87], v[86:87], v[102:103] op_sel_hi:[0,1]
	v_pk_mul_f32 v[92:93], v[92:93], v[100:101]
	v_pk_mul_f32 v[86:87], v[86:87], v[140:141]
	v_pk_mul_f32 v[92:93], v[8:9], v[92:93]
	v_pk_mul_f32 v[86:87], v[10:11], v[86:87]
	v_cvt_pk_bf16_f32 v92, v92, v93
	v_cvt_pk_bf16_f32 v93, v86, v87
	v_mul_f32_e32 v86, 0x45800000, v88
	v_cndmask_b32_e32 v86, v88, v86, vcc
	global_store_dwordx4 v[98:99], v[90:93], off
	v_or_b32_e32 v136, 28, v128
	s_nop 0
	v_mul_f32_e32 v90, 0x3f4ccccd, v86
	v_pk_mul_f32 v[86:87], v[90:91], v[134:135] op_sel_hi:[0,1]
	v_pk_mul_f32 v[92:93], v[90:91], v[96:97] op_sel_hi:[0,1]
	v_pk_mul_f32 v[86:87], v[86:87], v[162:163]
	v_pk_mul_f32 v[92:93], v[92:93], v[144:145]
	v_pk_mul_f32 v[86:87], v[12:13], v[86:87]
	v_pk_mul_f32 v[92:93], v[14:15], v[92:93]
	v_cvt_pk_bf16_f32 v86, v86, v87
	v_cvt_pk_bf16_f32 v87, v92, v93
	v_pk_mul_f32 v[92:93], v[90:91], v[132:133] op_sel_hi:[0,1]
	v_pk_mul_f32 v[92:93], v[92:93], v[142:143]
	v_pk_mul_f32 v[90:91], v[90:91], v[130:131] op_sel_hi:[0,1]
	v_pk_mul_f32 v[92:93], v[8:9], v[92:93]
	v_or_b32_e32 v132, 24, v128
	v_cvt_pk_bf16_f32 v88, v92, v93
	v_lshlrev_b32_e32 v92, 16, v89
	v_and_b32_e32 v93, 0xffff0000, v89
	v_pk_mul_f32 v[90:91], v[90:91], v[92:93]
	v_lshlrev_b32_e32 v130, 16, v85
	v_pk_mul_f32 v[90:91], v[10:11], v[90:91]
	v_and_b32_e32 v131, 0xffff0000, v85
	v_cvt_pk_bf16_f32 v89, v90, v91
	v_or_b32_e32 v90, s78, v164
	v_mov_b32_e32 v91, v2
	v_lshl_add_u64 v[90:91], v[90:91], 0, s[0:1]
	v_lshlrev_b64 v[90:91], 11, v[90:91]
	v_lshl_add_u64 v[90:91], s[38:39], 0, v[90:91]
	v_lshl_add_u64 v[94:95], v[90:91], 0, v[124:125]
	v_lshl_add_u32 v90, v132, 8, v129
	ds_read_b128 v[90:93], v90
	global_store_dwordx4 v[94:95], v[86:89], off
	v_and_b32_e32 v133, 0xffff0000, v6
	v_lshlrev_b32_e32 v134, 16, v5
	v_lshl_add_u32 v86, v136, 8, v129
	ds_read_b128 v[86:89], v86
	s_waitcnt lgkmcnt(1)
; __device__ __forceinline__ unsigned cvtpk(float lo, float hi) { return pg8::cvt_pk_bf16(lo, hi); }
; template <int VAR>
; __device__ __forceinline__ void dattn_block(const BlockRef& cur, const BlockRef& nxt, bool has_next, char* lds, Seam& S, const Outs& OU) {
;     ...
;         for (int i = 0; i < 8; ++i) { const int row = i * 4 + (lane_t >> 4);
;             const u32x4 v = *(const u32x4*)(stg + row * 128 + ch * 8);
;             float x0 = __builtin_bit_cast(float, v.x << 16), x1 = __builtin_bit_cast(float, v.x & 0xffff0000u), x2 = __builtin_bit_cast(float, v.y << 16), x3 = __builtin_bit_cast(float, v.y & 0xffff0000u);
;             float x4 = __builtin_bit_cast(float, v.z << 16), x5 = __builtin_bit_cast(float, v.z & 0xffff0000u), x6 = __builtin_bit_cast(float, v.w << 16), x7 = __builtin_bit_cast(float, v.w & 0xffff0000u);
;             float s = ((x0 * x0 + x1 * x1) + (x2 * x2 + x3 * x3)) + ((x4 * x4 + x5 * x5) + (x6 * x6 + x7 * x7));
;             s += __shfl_xor(s, 1); s += __shfl_xor(s, 2); s += __shfl_xor(s, 4); s += __shfl_xor(s, 8);
;             const float rn = rsqrtf(s * (1.f / 128.f) + EPS) * SC;
;             const u32x4 g = gsg[i];
;             u32x4 w;
;             w.x = cvtpk(x0 * rn * __builtin_bit_cast(float, g.x << 16) * sg0[0], x1 * rn * __builtin_bit_cast(float, g.x & 0xffff0000u) * sg0[1]);
;             w.y = cvtpk(x2 * rn * __builtin_bit_cast(float, g.y << 16) * sg0[2], x3 * rn * __builtin_bit_cast(float, g.y & 0xffff0000u) * sg0[3]);
;             w.z = cvtpk(x4 * rn * __builtin_bit_cast(float, g.z << 16) * sg1[0], x5 * rn * __builtin_bit_cast(float, g.z & 0xffff0000u) * sg1[1]);
;             w.w = cvtpk(x6 * rn * __builtin_bit_cast(float, g.w << 16) * sg1[2], x7 * rn * __builtin_bit_cast(float, g.w & 0xffff0000u) * sg1[3]);
;             *(u32x4*)(OU.BR + ((size_t)cur.m0 + wid * QBLK + row) * 1024 + cur.h * 128 + ch * 8) = w; }
	v_and_b32_e32 v95, 0xffff0000, v93
	v_and_b32_e32 v99, 0xffff0000, v91
	v_lshlrev_b32_e32 v94, 16, v93
	v_and_b32_e32 v97, 0xffff0000, v92
	v_lshlrev_b32_e32 v98, 16, v91
	v_and_b32_e32 v101, 0xffff0000, v90
	v_mov_b32_e32 v102, v99
	v_mov_b32_e32 v103, v95
	v_lshlrev_b32_e32 v96, 16, v92
	v_lshlrev_b32_e32 v100, 16, v90
	v_mov_b32_e32 v90, v98
	v_mov_b32_e32 v91, v94
	v_pk_mul_f32 v[102:103], v[102:103], v[102:103]
	v_mov_b32_e32 v104, v101
	v_mov_b32_e32 v105, v97
	v_pk_fma_f32 v[90:91], v[90:91], v[90:91], v[102:103]
	v_mov_b32_e32 v102, v100
	v_mov_b32_e32 v103, v96
	v_pk_mul_f32 v[104:105], v[104:105], v[104:105]
	s_waitcnt lgkmcnt(0)
	v_and_b32_e32 v109, 0xffff0000, v86
	v_pk_fma_f32 v[102:103], v[102:103], v[102:103], v[104:105]
	v_lshlrev_b32_e32 v104, 16, v88
	v_pk_add_f32 v[90:91], v[102:103], v[90:91]
	v_lshlrev_b32_e32 v102, 16, v89
	v_and_b32_e32 v103, 0xffff0000, v89
	v_and_b32_e32 v89, 0xffff0000, v87
	v_and_b32_e32 v105, 0xffff0000, v88
	v_lshlrev_b32_e32 v88, 16, v87
	v_mov_b32_e32 v126, v89
	v_mov_b32_e32 v127, v103
	v_lshlrev_b32_e32 v108, 16, v86
	v_mov_b32_e32 v86, v88
	v_mov_b32_e32 v87, v102
	v_pk_mul_f32 v[126:127], v[126:127], v[126:127]
	v_mov_b32_e32 v128, v109
	v_mov_b32_e32 v129, v105
	v_pk_fma_f32 v[86:87], v[86:87], v[86:87], v[126:127]
	v_mov_b32_e32 v126, v108
	v_mov_b32_e32 v127, v104
	v_pk_mul_f32 v[128:129], v[128:129], v[128:129]
	v_lshlrev_b32_e32 v92, 16, v84
	v_pk_fma_f32 v[126:127], v[126:127], v[126:127], v[128:129]
	v_and_b32_e32 v93, 0xffff0000, v84
	v_pk_add_f32 v[86:87], v[126:127], v[86:87]
	v_mov_b32_e32 v127, v90
	v_mov_b32_e32 v126, v86
	v_mov_b32_e32 v90, v87
	v_pk_add_f32 v[86:87], v[126:127], v[90:91]
	v_lshlrev_b32_e32 v126, 16, v83
	v_and_b32_e32 v127, 0xffff0000, v83
	v_lshlrev_b32_e32 v128, 16, v82
	v_and_b32_e32 v129, 0xffff0000, v82
	v_add_f32_dpp v86, v86, v86 quad_perm:[1,0,3,2] row_mask:0xf bank_mask:0xf
	v_add_f32_dpp v87, v87, v87 quad_perm:[1,0,3,2] row_mask:0xf bank_mask:0xf
	v_or_b32_e32 v82, s78, v132
	v_mov_b32_e32 v83, v2
	v_lshl_add_u64 v[82:83], v[82:83], 0, s[0:1]
	v_lshlrev_b64 v[82:83], 11, v[82:83]
	v_add_f32_dpp v84, v86, v86 quad_perm:[2,3,0,1] row_mask:0xf bank_mask:0xf
	v_add_f32_dpp v85, v87, v87 quad_perm:[2,3,0,1] row_mask:0xf bank_mask:0xf
	v_lshl_add_u64 v[82:83], s[38:39], 0, v[82:83]
	v_lshl_add_u64 v[90:91], v[82:83], 0, v[124:125]
	v_lshlrev_b32_e32 v132, 16, v6
	v_and_b32_e32 v135, 0xffff0000, v5
	v_add_f32_dpp v84, v84, v84 row_half_mirror row_mask:0xf bank_mask:0xf
	v_add_f32_dpp v85, v85, v85 row_half_mirror row_mask:0xf bank_mask:0xf
	s_nop 1
	v_add_f32_dpp v82, v84, v84 row_mirror row_mask:0xf bank_mask:0xf
	v_add_f32_dpp v83, v85, v85 row_mirror row_mask:0xf bank_mask:0xf
	s_nop 0
	v_pk_fma_f32 v[86:87], v[82:83], s[46:47], v[106:107] op_sel_hi:[1,0,0]
	v_lshlrev_b32_e32 v106, 16, v4
	v_mul_f32_e32 v6, 0x4b800000, v87
	v_cmp_gt_f32_e32 vcc, s77, v87
	v_and_b32_e32 v107, 0xffff0000, v4
	s_nop 0
	v_cndmask_b32_e32 v6, v87, v6, vcc
	v_rsq_f32_e32 v6, v6
	s_nop 0
	v_mul_f32_e32 v4, 0x45800000, v6
	v_cndmask_b32_e32 v4, v6, v4, vcc
	v_mul_f32_e32 v4, 0x3f4ccccd, v4
	v_pk_mul_f32 v[82:83], v[4:5], v[100:101] op_sel_hi:[0,1]
	v_pk_mul_f32 v[84:85], v[4:5], v[98:99] op_sel_hi:[0,1]
	v_mul_f32_e32 v6, 0x4b800000, v86
	v_cmp_gt_f32_e32 vcc, s77, v86
	v_pk_mul_f32 v[82:83], v[82:83], v[128:129]
	v_pk_mul_f32 v[84:85], v[84:85], v[126:127]
	v_cndmask_b32_e32 v6, v86, v6, vcc
	v_pk_mul_f32 v[82:83], v[12:13], v[82:83]
	v_pk_mul_f32 v[84:85], v[14:15], v[84:85]
	v_rsq_f32_e32 v6, v6
	v_cvt_pk_bf16_f32 v82, v82, v83
	v_cvt_pk_bf16_f32 v83, v84, v85
	v_pk_mul_f32 v[84:85], v[4:5], v[96:97] op_sel_hi:[0,1]
	v_pk_mul_f32 v[4:5], v[4:5], v[94:95] op_sel_hi:[0,1]
	v_pk_mul_f32 v[84:85], v[84:85], v[92:93]
	v_pk_mul_f32 v[4:5], v[4:5], v[130:131]
	v_pk_mul_f32 v[84:85], v[8:9], v[84:85]
	v_pk_mul_f32 v[4:5], v[10:11], v[4:5]
	v_cvt_pk_bf16_f32 v84, v84, v85
	v_cvt_pk_bf16_f32 v85, v4, v5
	v_mul_f32_e32 v4, 0x45800000, v6
	v_cndmask_b32_e32 v4, v6, v4, vcc
	global_store_dwordx4 v[90:91], v[82:85], off
	s_nop 1
	v_mul_f32_e32 v82, 0x3f4ccccd, v4
	v_pk_mul_f32 v[4:5], v[82:83], v[108:109] op_sel_hi:[0,1]
	v_pk_mul_f32 v[4:5], v[4:5], v[106:107]
	s_nop 0
	v_pk_mul_f32 v[4:5], v[12:13], v[4:5]
	v_pk_mul_f32 v[12:13], v[82:83], v[88:89] op_sel_hi:[0,1]
	v_pk_mul_f32 v[12:13], v[12:13], v[134:135]
	v_cvt_pk_bf16_f32 v4, v4, v5
	v_pk_mul_f32 v[12:13], v[14:15], v[12:13]
	s_nop 0
	v_cvt_pk_bf16_f32 v5, v12, v13
	v_pk_mul_f32 v[12:13], v[82:83], v[104:105] op_sel_hi:[0,1]
	v_pk_mul_f32 v[12:13], v[12:13], v[132:133]
	s_nop 0
	v_pk_mul_f32 v[8:9], v[8:9], v[12:13]
	v_lshlrev_b32_e32 v12, 16, v7
	v_cvt_pk_bf16_f32 v6, v8, v9
	v_pk_mul_f32 v[8:9], v[82:83], v[102:103] op_sel_hi:[0,1]
	v_and_b32_e32 v13, 0xffff0000, v7
	v_pk_mul_f32 v[8:9], v[8:9], v[12:13]
	s_nop 0
	v_pk_mul_f32 v[8:9], v[10:11], v[8:9]
	s_nop 0
	v_cvt_pk_bf16_f32 v7, v8, v9
	v_or_b32_e32 v8, s78, v136
	v_mov_b32_e32 v9, v2
	v_lshl_add_u64 v[8:9], v[8:9], 0, s[0:1]
	v_lshlrev_b64 v[8:9], 11, v[8:9]
	v_lshl_add_u64 v[8:9], s[38:39], 0, v[8:9]
	v_lshl_add_u64 v[8:9], v[8:9], 0, v[124:125]
	global_store_dwordx4 v[8:9], v[4:7], off
	s_cbranch_execnz .LBB0_345
	s_branch .LBB0_459
